# v38: v37 plus packed f32 (v_pk_mul_f32/v_pk_add_f32) for gate scaling, sigmoid denominator and gate*sigmoid of neighbouring SwiGLU outputs; same f32 arithmetic
# speedup vs baseline: 1.0062x; 1.0033x over previous
.Lpeel_exit_2:
	s_mov_b32 s98, 0x3b000000
	s_mov_b32 s99, 0xbcb8aa3b
	s_mov_b32 s100, 1.0
	v_pk_mul_f32 v[236:237], v[158:159], s[98:99] op_sel_hi:[1,0]
	v_pk_mul_f32 v[234:235], v[158:159], s[98:99] op_sel:[0,1] op_sel_hi:[1,1]
	v_exp_f32_e32 v234, v234
	v_exp_f32_e32 v235, v235
	s_nop 0
	v_pk_add_f32 v[234:235], v[234:235], s[100:101] op_sel_hi:[1,0]
	v_rcp_f32_e32 v234, v234
	v_rcp_f32_e32 v235, v235
	s_nop 0
	v_pk_mul_f32 v[236:237], v[236:237], v[234:235]
	s_ashr_i32 s29, s28, 31
	s_ashr_i32 s27, s26, 31
	s_lshl_b64 s[10:11], s[28:29], 18
	s_lshl_b64 s[26:27], s[26:27], 15
	v_mov_b32_e32 v3, v195
	s_add_u32 s0, s6, s10
	v_mul_f32_e32 v5, v236, v154
	v_med3_f32 v5, v5, s40, v190
	s_nop 15
	s_nop 15
	v_mov_b32_e32 v2, v196
	v_pk_mul_f32 v[238:239], v[160:161], s[98:99] op_sel_hi:[1,0]
	v_pk_mul_f32 v[234:235], v[160:161], s[98:99] op_sel:[0,1] op_sel_hi:[1,1]
	v_exp_f32_e32 v234, v234
	v_exp_f32_e32 v235, v235
	s_nop 0
	v_pk_add_f32 v[234:235], v[234:235], s[100:101] op_sel_hi:[1,0]
	v_rcp_f32_e32 v234, v234
	v_rcp_f32_e32 v235, v235
	s_nop 0
	v_pk_mul_f32 v[238:239], v[238:239], v[234:235]
	v_mul_f32_e32 v6, v237, v155
	v_add_u32_e32 v4, s49, v3
	s_addc_u32 s1, s7, s11
	s_add_u32 s10, s0, s26
	v_mul_f32_e32 v7, v238, v156
	v_lshl_add_u32 v2, v2, 3, s50
	s_addc_u32 s11, s1, s27
	v_ashrrev_i32_e32 v3, 31, v2
	s_and_b64 vcc, exec, s[8:9]
	v_pk_mul_f32 v[240:241], v[150:151], s[98:99] op_sel_hi:[1,0]
	v_pk_mul_f32 v[234:235], v[150:151], s[98:99] op_sel:[0,1] op_sel_hi:[1,1]
	v_exp_f32_e32 v234, v234
	v_exp_f32_e32 v235, v235
	s_nop 0
	v_pk_add_f32 v[234:235], v[234:235], s[100:101] op_sel_hi:[1,0]
	v_rcp_f32_e32 v234, v234
	v_rcp_f32_e32 v235, v235
	s_nop 0
	v_pk_mul_f32 v[240:241], v[240:241], v[234:235]
	v_mul_f32_e32 v8, v239, v157
	v_mov_b32_e32 v174, v200
	v_mov_b32_e32 v172, v199
	v_mov_b32_e32 v170, v198
	v_mov_b32_e32 v168, v171
	v_mul_f32_e32 v9, v240, v146
	s_mov_b32 s26, s24
	s_mov_b32 s28, s54
	s_mov_b64 s[30:31], s[12:13]
	v_pk_mul_f32 v[242:243], v[152:153], s[98:99] op_sel_hi:[1,0]
	v_pk_mul_f32 v[234:235], v[152:153], s[98:99] op_sel:[0,1] op_sel_hi:[1,1]
	v_exp_f32_e32 v234, v234
	v_exp_f32_e32 v235, v235
	s_nop 0
	v_pk_add_f32 v[234:235], v[234:235], s[100:101] op_sel_hi:[1,0]
	v_rcp_f32_e32 v234, v234
	v_rcp_f32_e32 v235, v235
	s_nop 0
	v_pk_mul_f32 v[242:243], v[242:243], v[234:235]
	v_mul_f32_e32 v10, v241, v147
	s_nop 0
	v_mul_f32_e32 v11, v242, v148
	s_nop 0
	v_med3_f32 v13, v6, s40, v190
	v_mov_b32_e32 v6, v163
	v_cvt_pk_fp8_f32 v6, v5, v13
	v_med3_f32 v5, v7, s40, v190
	v_med3_f32 v7, v8, s40, v190
	v_med3_f32 v8, v10, s40, v190
	v_cvt_pk_fp8_f32 v6, v5, v7 op_sel:[0,0,1]
	v_med3_f32 v5, v9, s40, v190
	v_mov_b32_e32 v7, v163
	v_cvt_pk_fp8_f32 v7, v5, v8
	v_mul_f32_e32 v12, v243, v149
	v_med3_f32 v5, v11, s40, v190
	v_med3_f32 v8, v12, s40, v190
	v_cvt_pk_fp8_f32 v7, v5, v8 op_sel:[0,0,1]
	v_ashrrev_i32_e32 v5, 31, v4
	v_lshlrev_b64 v[8:9], 7, v[4:5]
	v_lshl_add_u64 v[8:9], s[10:11], 0, v[8:9]
	v_lshl_add_u64 v[8:9], v[8:9], 0, v[2:3]
	v_pk_mul_f32 v[244:245], v[142:143], s[98:99] op_sel_hi:[1,0]
	v_pk_mul_f32 v[234:235], v[142:143], s[98:99] op_sel:[0,1] op_sel_hi:[1,1]
	v_exp_f32_e32 v234, v234
	v_exp_f32_e32 v235, v235
	s_nop 0
	v_pk_add_f32 v[234:235], v[234:235], s[100:101] op_sel_hi:[1,0]
	v_rcp_f32_e32 v234, v234
	v_rcp_f32_e32 v235, v235
	s_nop 0
	v_pk_mul_f32 v[244:245], v[244:245], v[234:235]
	global_store_dwordx2 v[8:9], v[6:7], off
	s_nop 0
	s_nop 0
	v_mul_f32_e32 v5, v244, v138
	v_med3_f32 v5, v5, s40, v190
	s_nop 0
	v_mul_f32_e32 v7, v245, v139
	v_pk_mul_f32 v[246:247], v[144:145], s[98:99] op_sel_hi:[1,0]
	v_pk_mul_f32 v[234:235], v[144:145], s[98:99] op_sel:[0,1] op_sel_hi:[1,1]
	v_exp_f32_e32 v234, v234
	v_exp_f32_e32 v235, v235
	s_nop 0
	v_pk_add_f32 v[234:235], v[234:235], s[100:101] op_sel_hi:[1,0]
	v_rcp_f32_e32 v234, v234
	v_rcp_f32_e32 v235, v235
	s_nop 0
	v_pk_mul_f32 v[246:247], v[246:247], v[234:235]
	v_med3_f32 v7, v7, s40, v190
	s_nop 0
	v_mul_f32_e32 v9, v246, v140
	s_nop 0
	s_nop 0
	v_mul_f32_e32 v10, v247, v141
	v_pk_mul_f32 v[248:249], v[134:135], s[98:99] op_sel_hi:[1,0]
	v_pk_mul_f32 v[234:235], v[134:135], s[98:99] op_sel:[0,1] op_sel_hi:[1,1]
	v_exp_f32_e32 v234, v234
	v_exp_f32_e32 v235, v235
	s_nop 0
	v_pk_add_f32 v[234:235], v[234:235], s[100:101] op_sel_hi:[1,0]
	v_rcp_f32_e32 v234, v234
	v_rcp_f32_e32 v235, v235
	s_nop 0
	v_pk_mul_f32 v[248:249], v[248:249], v[234:235]
	s_nop 0
	s_nop 0
	v_mul_f32_e32 v11, v248, v130
	s_nop 0
	s_nop 0
	v_mul_f32_e32 v12, v249, v131
	v_pk_mul_f32 v[250:251], v[136:137], s[98:99] op_sel_hi:[1,0]
	v_pk_mul_f32 v[234:235], v[136:137], s[98:99] op_sel:[0,1] op_sel_hi:[1,1]
	v_exp_f32_e32 v234, v234
	v_exp_f32_e32 v235, v235
	s_nop 0
	v_pk_add_f32 v[234:235], v[234:235], s[100:101] op_sel_hi:[1,0]
	v_rcp_f32_e32 v234, v234
	v_rcp_f32_e32 v235, v235
	s_nop 0
	v_pk_mul_f32 v[250:251], v[250:251], v[234:235]
	s_nop 0
	s_nop 0
	v_mul_f32_e32 v13, v250, v132
	s_nop 0
	s_nop 0
	v_mov_b32_e32 v8, v163
	v_cvt_pk_fp8_f32 v8, v5, v7
	v_med3_f32 v5, v9, s40, v190
	v_med3_f32 v7, v10, s40, v190
	v_mov_b32_e32 v9, v163
	v_cvt_pk_fp8_f32 v8, v5, v7 op_sel:[0,0,1]
	v_med3_f32 v5, v11, s40, v190
	v_med3_f32 v7, v12, s40, v190
	v_cvt_pk_fp8_f32 v9, v5, v7
	v_mul_f32_e32 v14, v251, v133
	v_add_u32_e32 v6, 16, v4
	v_med3_f32 v5, v13, s40, v190
	v_med3_f32 v7, v14, s40, v190
	v_cvt_pk_fp8_f32 v9, v5, v7 op_sel:[0,0,1]
	v_ashrrev_i32_e32 v7, 31, v6
	v_lshlrev_b64 v[6:7], 7, v[6:7]
	v_lshl_add_u64 v[6:7], s[10:11], 0, v[6:7]
	v_lshl_add_u64 v[6:7], v[6:7], 0, v[2:3]
	v_pk_mul_f32 v[236:237], v[126:127], s[98:99] op_sel_hi:[1,0]
	v_pk_mul_f32 v[234:235], v[126:127], s[98:99] op_sel:[0,1] op_sel_hi:[1,1]
	v_exp_f32_e32 v234, v234
	v_exp_f32_e32 v235, v235
	s_nop 0
	v_pk_add_f32 v[234:235], v[234:235], s[100:101] op_sel_hi:[1,0]
	v_rcp_f32_e32 v234, v234
	v_rcp_f32_e32 v235, v235
	s_nop 0
	v_pk_mul_f32 v[236:237], v[236:237], v[234:235]
	global_store_dwordx2 v[6:7], v[8:9], off
	s_nop 0
	s_nop 0
	v_mul_f32_e32 v5, v236, v122
	v_med3_f32 v5, v5, s40, v190
	s_nop 0
	v_mul_f32_e32 v7, v237, v123
	v_pk_mul_f32 v[238:239], v[128:129], s[98:99] op_sel_hi:[1,0]
	v_pk_mul_f32 v[234:235], v[128:129], s[98:99] op_sel:[0,1] op_sel_hi:[1,1]
	v_exp_f32_e32 v234, v234
	v_exp_f32_e32 v235, v235
	s_nop 0
	v_pk_add_f32 v[234:235], v[234:235], s[100:101] op_sel_hi:[1,0]
	v_rcp_f32_e32 v234, v234
	v_rcp_f32_e32 v235, v235
	s_nop 0
	v_pk_mul_f32 v[238:239], v[238:239], v[234:235]
	v_med3_f32 v7, v7, s40, v190
	s_nop 0
	v_mul_f32_e32 v9, v238, v124
	s_nop 0
	s_nop 0
	v_mul_f32_e32 v10, v239, v125
	v_pk_mul_f32 v[240:241], v[118:119], s[98:99] op_sel_hi:[1,0]
	v_pk_mul_f32 v[234:235], v[118:119], s[98:99] op_sel:[0,1] op_sel_hi:[1,1]
	v_exp_f32_e32 v234, v234
	v_exp_f32_e32 v235, v235
	s_nop 0
	v_pk_add_f32 v[234:235], v[234:235], s[100:101] op_sel_hi:[1,0]
	v_rcp_f32_e32 v234, v234
	v_rcp_f32_e32 v235, v235
	s_nop 0
	v_pk_mul_f32 v[240:241], v[240:241], v[234:235]
	s_nop 0
	s_nop 0
	v_mul_f32_e32 v11, v240, v114
	s_nop 0
	s_nop 0
	v_mul_f32_e32 v12, v241, v115
	v_pk_mul_f32 v[242:243], v[120:121], s[98:99] op_sel_hi:[1,0]
	v_pk_mul_f32 v[234:235], v[120:121], s[98:99] op_sel:[0,1] op_sel_hi:[1,1]
	v_exp_f32_e32 v234, v234
	v_exp_f32_e32 v235, v235
	s_nop 0
	v_pk_add_f32 v[234:235], v[234:235], s[100:101] op_sel_hi:[1,0]
	v_rcp_f32_e32 v234, v234
	v_rcp_f32_e32 v235, v235
	s_nop 0
	v_pk_mul_f32 v[242:243], v[242:243], v[234:235]
	s_nop 0
	s_nop 0
	v_mul_f32_e32 v13, v242, v116
	s_nop 0
	s_nop 0
	v_mov_b32_e32 v8, v163
	v_cvt_pk_fp8_f32 v8, v5, v7
	v_med3_f32 v5, v9, s40, v190
	v_med3_f32 v7, v10, s40, v190
	v_mov_b32_e32 v9, v163
	v_cvt_pk_fp8_f32 v8, v5, v7 op_sel:[0,0,1]
	v_med3_f32 v5, v11, s40, v190
	v_med3_f32 v7, v12, s40, v190
	v_cvt_pk_fp8_f32 v9, v5, v7
	v_mul_f32_e32 v14, v243, v117
	v_add_u32_e32 v6, 32, v4
	v_med3_f32 v5, v13, s40, v190
	v_med3_f32 v7, v14, s40, v190
	v_cvt_pk_fp8_f32 v9, v5, v7 op_sel:[0,0,1]
	v_ashrrev_i32_e32 v7, 31, v6
	v_lshlrev_b64 v[6:7], 7, v[6:7]
	v_lshl_add_u64 v[6:7], s[10:11], 0, v[6:7]
	v_lshl_add_u64 v[6:7], v[6:7], 0, v[2:3]
	v_pk_mul_f32 v[244:245], v[110:111], s[98:99] op_sel_hi:[1,0]
	v_pk_mul_f32 v[234:235], v[110:111], s[98:99] op_sel:[0,1] op_sel_hi:[1,1]
	v_exp_f32_e32 v234, v234
	v_exp_f32_e32 v235, v235
	s_nop 0
	v_pk_add_f32 v[234:235], v[234:235], s[100:101] op_sel_hi:[1,0]
	v_rcp_f32_e32 v234, v234
	v_rcp_f32_e32 v235, v235
	s_nop 0
	v_pk_mul_f32 v[244:245], v[244:245], v[234:235]
	global_store_dwordx2 v[6:7], v[8:9], off
	s_nop 0
	s_nop 0
	v_mul_f32_e32 v5, v244, v106
	v_med3_f32 v5, v5, s40, v190
	s_nop 0
	v_mul_f32_e32 v7, v245, v107
	v_pk_mul_f32 v[246:247], v[112:113], s[98:99] op_sel_hi:[1,0]
	v_pk_mul_f32 v[234:235], v[112:113], s[98:99] op_sel:[0,1] op_sel_hi:[1,1]
	v_exp_f32_e32 v234, v234
	v_exp_f32_e32 v235, v235
	s_nop 0
	v_pk_add_f32 v[234:235], v[234:235], s[100:101] op_sel_hi:[1,0]
	v_rcp_f32_e32 v234, v234
	v_rcp_f32_e32 v235, v235
	s_nop 0
	v_pk_mul_f32 v[246:247], v[246:247], v[234:235]
	v_med3_f32 v7, v7, s40, v190
	s_nop 0
	v_mul_f32_e32 v9, v246, v108
	s_nop 0
	s_nop 0
	v_mul_f32_e32 v10, v247, v109
	v_pk_mul_f32 v[248:249], v[102:103], s[98:99] op_sel_hi:[1,0]
	v_pk_mul_f32 v[234:235], v[102:103], s[98:99] op_sel:[0,1] op_sel_hi:[1,1]
	v_exp_f32_e32 v234, v234
	v_exp_f32_e32 v235, v235
	s_nop 0
	v_pk_add_f32 v[234:235], v[234:235], s[100:101] op_sel_hi:[1,0]
	v_rcp_f32_e32 v234, v234
	v_rcp_f32_e32 v235, v235
	s_nop 0
	v_pk_mul_f32 v[248:249], v[248:249], v[234:235]
	s_nop 0
	s_nop 0
	v_mul_f32_e32 v11, v248, v98
	s_nop 0
	s_nop 0
	v_mul_f32_e32 v12, v249, v99
	v_pk_mul_f32 v[250:251], v[104:105], s[98:99] op_sel_hi:[1,0]
	v_pk_mul_f32 v[234:235], v[104:105], s[98:99] op_sel:[0,1] op_sel_hi:[1,1]
	v_exp_f32_e32 v234, v234
	v_exp_f32_e32 v235, v235
	s_nop 0
	v_pk_add_f32 v[234:235], v[234:235], s[100:101] op_sel_hi:[1,0]
	v_rcp_f32_e32 v234, v234
	v_rcp_f32_e32 v235, v235
	s_nop 0
	v_pk_mul_f32 v[250:251], v[250:251], v[234:235]
	s_nop 0
	s_nop 0
	v_mul_f32_e32 v13, v250, v100
	s_nop 0
	s_nop 0
	v_mov_b32_e32 v8, v163
	v_cvt_pk_fp8_f32 v8, v5, v7
	v_med3_f32 v5, v9, s40, v190
	v_med3_f32 v7, v10, s40, v190
	v_mov_b32_e32 v9, v163
	v_cvt_pk_fp8_f32 v8, v5, v7 op_sel:[0,0,1]
	v_med3_f32 v5, v11, s40, v190
	v_med3_f32 v7, v12, s40, v190
	v_cvt_pk_fp8_f32 v9, v5, v7
	v_mul_f32_e32 v14, v251, v101
	v_add_u32_e32 v6, 48, v4
	v_med3_f32 v5, v13, s40, v190
	v_med3_f32 v7, v14, s40, v190
	v_cvt_pk_fp8_f32 v9, v5, v7 op_sel:[0,0,1]
	v_ashrrev_i32_e32 v7, 31, v6
	v_lshlrev_b64 v[6:7], 7, v[6:7]
	v_lshl_add_u64 v[6:7], s[10:11], 0, v[6:7]
	v_lshl_add_u64 v[6:7], v[6:7], 0, v[2:3]
	v_pk_mul_f32 v[236:237], v[94:95], s[98:99] op_sel_hi:[1,0]
	v_pk_mul_f32 v[234:235], v[94:95], s[98:99] op_sel:[0,1] op_sel_hi:[1,1]
	v_exp_f32_e32 v234, v234
	v_exp_f32_e32 v235, v235
	s_nop 0
	v_pk_add_f32 v[234:235], v[234:235], s[100:101] op_sel_hi:[1,0]
	v_rcp_f32_e32 v234, v234
	v_rcp_f32_e32 v235, v235
	s_nop 0
	v_pk_mul_f32 v[236:237], v[236:237], v[234:235]
	global_store_dwordx2 v[6:7], v[8:9], off
	v_add_u32_e32 v6, 0x80, v4
	s_nop 0
	v_mul_f32_e32 v5, v236, v90
	v_med3_f32 v5, v5, s40, v190
	s_nop 0
	v_pk_mul_f32 v[238:239], v[96:97], s[98:99] op_sel_hi:[1,0]
	v_pk_mul_f32 v[234:235], v[96:97], s[98:99] op_sel:[0,1] op_sel_hi:[1,1]
	v_exp_f32_e32 v234, v234
	v_exp_f32_e32 v235, v235
	s_nop 0
	v_pk_add_f32 v[234:235], v[234:235], s[100:101] op_sel_hi:[1,0]
	v_rcp_f32_e32 v234, v234
	v_rcp_f32_e32 v235, v235
	s_nop 0
	v_pk_mul_f32 v[238:239], v[238:239], v[234:235]
	v_mul_f32_e32 v7, v237, v91
	v_med3_f32 v7, v7, s40, v190
	s_nop 0
	v_mul_f32_e32 v9, v238, v92
	s_nop 0
	s_nop 0
	v_mul_f32_e32 v10, v239, v93
	v_pk_mul_f32 v[240:241], v[86:87], s[98:99] op_sel_hi:[1,0]
	v_pk_mul_f32 v[234:235], v[86:87], s[98:99] op_sel:[0,1] op_sel_hi:[1,1]
	v_exp_f32_e32 v234, v234
	v_exp_f32_e32 v235, v235
	s_nop 0
	v_pk_add_f32 v[234:235], v[234:235], s[100:101] op_sel_hi:[1,0]
	v_rcp_f32_e32 v234, v234
	v_rcp_f32_e32 v235, v235
	s_nop 0
	v_pk_mul_f32 v[240:241], v[240:241], v[234:235]
	s_nop 0
	s_nop 0
	v_mul_f32_e32 v11, v240, v82
	s_nop 0
	s_nop 0
	v_mul_f32_e32 v12, v241, v83
	v_pk_mul_f32 v[242:243], v[88:89], s[98:99] op_sel_hi:[1,0]
	v_pk_mul_f32 v[234:235], v[88:89], s[98:99] op_sel:[0,1] op_sel_hi:[1,1]
	v_exp_f32_e32 v234, v234
	v_exp_f32_e32 v235, v235
	s_nop 0
	v_pk_add_f32 v[234:235], v[234:235], s[100:101] op_sel_hi:[1,0]
	v_rcp_f32_e32 v234, v234
	v_rcp_f32_e32 v235, v235
	s_nop 0
	v_pk_mul_f32 v[242:243], v[242:243], v[234:235]
	s_nop 0
	s_nop 0
	v_mul_f32_e32 v13, v242, v84
	s_nop 0
	s_nop 0
	v_mul_f32_e32 v14, v243, v85
	v_mov_b32_e32 v8, v163
	v_cvt_pk_fp8_f32 v8, v5, v7
	v_med3_f32 v5, v9, s40, v190
	v_med3_f32 v7, v10, s40, v190
	v_mov_b32_e32 v9, v163
	v_cvt_pk_fp8_f32 v8, v5, v7 op_sel:[0,0,1]
	v_med3_f32 v5, v11, s40, v190
	v_med3_f32 v7, v12, s40, v190
	v_cvt_pk_fp8_f32 v9, v5, v7
	v_med3_f32 v5, v13, s40, v190
	v_med3_f32 v7, v14, s40, v190
	v_cvt_pk_fp8_f32 v9, v5, v7 op_sel:[0,0,1]
	v_ashrrev_i32_e32 v7, 31, v6
	v_lshlrev_b64 v[6:7], 7, v[6:7]
	v_lshl_add_u64 v[6:7], s[10:11], 0, v[6:7]
	v_lshl_add_u64 v[6:7], v[6:7], 0, v[2:3]
	v_pk_mul_f32 v[244:245], v[78:79], s[98:99] op_sel_hi:[1,0]
	v_pk_mul_f32 v[234:235], v[78:79], s[98:99] op_sel:[0,1] op_sel_hi:[1,1]
	v_exp_f32_e32 v234, v234
	v_exp_f32_e32 v235, v235
	s_nop 0
	v_pk_add_f32 v[234:235], v[234:235], s[100:101] op_sel_hi:[1,0]
	v_rcp_f32_e32 v234, v234
	v_rcp_f32_e32 v235, v235
	s_nop 0
	v_pk_mul_f32 v[244:245], v[244:245], v[234:235]
	global_store_dwordx2 v[6:7], v[8:9], off
	s_nop 0
	s_nop 0
	v_mul_f32_e32 v5, v244, v74
	v_med3_f32 v5, v5, s40, v190
	s_nop 0
	v_mul_f32_e32 v7, v245, v75
	v_pk_mul_f32 v[246:247], v[80:81], s[98:99] op_sel_hi:[1,0]
	v_pk_mul_f32 v[234:235], v[80:81], s[98:99] op_sel:[0,1] op_sel_hi:[1,1]
	v_exp_f32_e32 v234, v234
	v_exp_f32_e32 v235, v235
	s_nop 0
	v_pk_add_f32 v[234:235], v[234:235], s[100:101] op_sel_hi:[1,0]
	v_rcp_f32_e32 v234, v234
	v_rcp_f32_e32 v235, v235
	s_nop 0
	v_pk_mul_f32 v[246:247], v[246:247], v[234:235]
	v_med3_f32 v7, v7, s40, v190
	s_nop 0
	v_mul_f32_e32 v9, v246, v76
	s_nop 0
	s_nop 0
	v_mul_f32_e32 v10, v247, v77
	v_pk_mul_f32 v[248:249], v[70:71], s[98:99] op_sel_hi:[1,0]
	v_pk_mul_f32 v[234:235], v[70:71], s[98:99] op_sel:[0,1] op_sel_hi:[1,1]
	v_exp_f32_e32 v234, v234
	v_exp_f32_e32 v235, v235
	s_nop 0
	v_pk_add_f32 v[234:235], v[234:235], s[100:101] op_sel_hi:[1,0]
	v_rcp_f32_e32 v234, v234
	v_rcp_f32_e32 v235, v235
	s_nop 0
	v_pk_mul_f32 v[248:249], v[248:249], v[234:235]
	s_nop 0
	s_nop 0
	v_mul_f32_e32 v11, v248, v66
	s_nop 0
	s_nop 0
	v_mul_f32_e32 v12, v249, v67
	v_pk_mul_f32 v[250:251], v[72:73], s[98:99] op_sel_hi:[1,0]
	v_pk_mul_f32 v[234:235], v[72:73], s[98:99] op_sel:[0,1] op_sel_hi:[1,1]
	v_exp_f32_e32 v234, v234
	v_exp_f32_e32 v235, v235
	s_nop 0
	v_pk_add_f32 v[234:235], v[234:235], s[100:101] op_sel_hi:[1,0]
	v_rcp_f32_e32 v234, v234
	v_rcp_f32_e32 v235, v235
	s_nop 0
	v_pk_mul_f32 v[250:251], v[250:251], v[234:235]
	s_nop 0
	s_nop 0
	v_mul_f32_e32 v13, v250, v68
	s_nop 0
	s_nop 0
	v_mov_b32_e32 v8, v163
	v_cvt_pk_fp8_f32 v8, v5, v7
	v_med3_f32 v5, v9, s40, v190
	v_med3_f32 v7, v10, s40, v190
	v_mov_b32_e32 v9, v163
	v_cvt_pk_fp8_f32 v8, v5, v7 op_sel:[0,0,1]
	v_med3_f32 v5, v11, s40, v190
	v_med3_f32 v7, v12, s40, v190
	v_cvt_pk_fp8_f32 v9, v5, v7
	v_mul_f32_e32 v14, v251, v69
	v_add_u32_e32 v6, 0x90, v4
	v_med3_f32 v5, v13, s40, v190
	v_med3_f32 v7, v14, s40, v190
	v_cvt_pk_fp8_f32 v9, v5, v7 op_sel:[0,0,1]
	v_ashrrev_i32_e32 v7, 31, v6
	v_lshlrev_b64 v[6:7], 7, v[6:7]
	v_lshl_add_u64 v[6:7], s[10:11], 0, v[6:7]
	v_lshl_add_u64 v[6:7], v[6:7], 0, v[2:3]
	v_pk_mul_f32 v[236:237], v[62:63], s[98:99] op_sel_hi:[1,0]
	v_pk_mul_f32 v[234:235], v[62:63], s[98:99] op_sel:[0,1] op_sel_hi:[1,1]
	v_exp_f32_e32 v234, v234
	v_exp_f32_e32 v235, v235
	s_nop 0
	v_pk_add_f32 v[234:235], v[234:235], s[100:101] op_sel_hi:[1,0]
	v_rcp_f32_e32 v234, v234
	v_rcp_f32_e32 v235, v235
	s_nop 0
	v_pk_mul_f32 v[236:237], v[236:237], v[234:235]
	global_store_dwordx2 v[6:7], v[8:9], off
	s_nop 0
	s_nop 0
	v_mul_f32_e32 v5, v236, v58
	v_med3_f32 v5, v5, s40, v190
	s_nop 0
	v_mul_f32_e32 v7, v237, v59
	v_pk_mul_f32 v[238:239], v[64:65], s[98:99] op_sel_hi:[1,0]
	v_pk_mul_f32 v[234:235], v[64:65], s[98:99] op_sel:[0,1] op_sel_hi:[1,1]
	v_exp_f32_e32 v234, v234
	v_exp_f32_e32 v235, v235
	s_nop 0
	v_pk_add_f32 v[234:235], v[234:235], s[100:101] op_sel_hi:[1,0]
	v_rcp_f32_e32 v234, v234
	v_rcp_f32_e32 v235, v235
	s_nop 0
	v_pk_mul_f32 v[238:239], v[238:239], v[234:235]
	v_med3_f32 v7, v7, s40, v190
	s_nop 0
	v_mul_f32_e32 v9, v238, v60
	s_nop 0
	s_nop 0
	v_mul_f32_e32 v10, v239, v61
	v_pk_mul_f32 v[240:241], v[54:55], s[98:99] op_sel_hi:[1,0]
	v_pk_mul_f32 v[234:235], v[54:55], s[98:99] op_sel:[0,1] op_sel_hi:[1,1]
	v_exp_f32_e32 v234, v234
	v_exp_f32_e32 v235, v235
	s_nop 0
	v_pk_add_f32 v[234:235], v[234:235], s[100:101] op_sel_hi:[1,0]
	v_rcp_f32_e32 v234, v234
	v_rcp_f32_e32 v235, v235
	s_nop 0
	v_pk_mul_f32 v[240:241], v[240:241], v[234:235]
	s_nop 0
	s_nop 0
	v_mul_f32_e32 v11, v240, v50
	s_nop 0
	s_nop 0
	v_mul_f32_e32 v12, v241, v51
	v_pk_mul_f32 v[242:243], v[56:57], s[98:99] op_sel_hi:[1,0]
	v_pk_mul_f32 v[234:235], v[56:57], s[98:99] op_sel:[0,1] op_sel_hi:[1,1]
	v_exp_f32_e32 v234, v234
	v_exp_f32_e32 v235, v235
	s_nop 0
	v_pk_add_f32 v[234:235], v[234:235], s[100:101] op_sel_hi:[1,0]
	v_rcp_f32_e32 v234, v234
	v_rcp_f32_e32 v235, v235
	s_nop 0
	v_pk_mul_f32 v[242:243], v[242:243], v[234:235]
	s_nop 0
	s_nop 0
	v_mul_f32_e32 v13, v242, v52
	s_nop 0
	s_nop 0
	v_mov_b32_e32 v8, v163
	v_cvt_pk_fp8_f32 v8, v5, v7
	v_med3_f32 v5, v9, s40, v190
	v_med3_f32 v7, v10, s40, v190
	v_mov_b32_e32 v9, v163
	v_cvt_pk_fp8_f32 v8, v5, v7 op_sel:[0,0,1]
	v_med3_f32 v5, v11, s40, v190
	v_med3_f32 v7, v12, s40, v190
	v_cvt_pk_fp8_f32 v9, v5, v7
	v_mul_f32_e32 v14, v243, v53
	v_add_u32_e32 v6, 0xa0, v4
	v_med3_f32 v5, v13, s40, v190
	v_med3_f32 v7, v14, s40, v190
	v_cvt_pk_fp8_f32 v9, v5, v7 op_sel:[0,0,1]
	v_ashrrev_i32_e32 v7, 31, v6
	v_lshlrev_b64 v[6:7], 7, v[6:7]
	v_lshl_add_u64 v[6:7], s[10:11], 0, v[6:7]
	v_lshl_add_u64 v[6:7], v[6:7], 0, v[2:3]
	v_pk_mul_f32 v[244:245], v[46:47], s[98:99] op_sel_hi:[1,0]
	v_pk_mul_f32 v[234:235], v[46:47], s[98:99] op_sel:[0,1] op_sel_hi:[1,1]
	v_exp_f32_e32 v234, v234
	v_exp_f32_e32 v235, v235
	s_nop 0
	v_pk_add_f32 v[234:235], v[234:235], s[100:101] op_sel_hi:[1,0]
	v_rcp_f32_e32 v234, v234
	v_rcp_f32_e32 v235, v235
	s_nop 0
	v_pk_mul_f32 v[244:245], v[244:245], v[234:235]
	global_store_dwordx2 v[6:7], v[8:9], off
	v_add_u32_e32 v4, 0xb0, v4
	s_nop 0
	v_mul_f32_e32 v5, v244, v42
	v_med3_f32 v5, v5, s40, v190
	s_nop 0
	v_pk_mul_f32 v[246:247], v[48:49], s[98:99] op_sel_hi:[1,0]
	v_pk_mul_f32 v[234:235], v[48:49], s[98:99] op_sel:[0,1] op_sel_hi:[1,1]
	v_exp_f32_e32 v234, v234
	v_exp_f32_e32 v235, v235
	s_nop 0
	v_pk_add_f32 v[234:235], v[234:235], s[100:101] op_sel_hi:[1,0]
	v_rcp_f32_e32 v234, v234
	v_rcp_f32_e32 v235, v235
	s_nop 0
	v_pk_mul_f32 v[246:247], v[246:247], v[234:235]
	v_mul_f32_e32 v6, v245, v43
	s_nop 0
	v_mul_f32_e32 v7, v246, v44
	s_nop 0
	v_pk_mul_f32 v[248:249], v[38:39], s[98:99] op_sel_hi:[1,0]
	v_pk_mul_f32 v[234:235], v[38:39], s[98:99] op_sel:[0,1] op_sel_hi:[1,1]
	v_exp_f32_e32 v234, v234
	v_exp_f32_e32 v235, v235
	s_nop 0
	v_pk_add_f32 v[234:235], v[234:235], s[100:101] op_sel_hi:[1,0]
	v_rcp_f32_e32 v234, v234
	v_rcp_f32_e32 v235, v235
	s_nop 0
	v_pk_mul_f32 v[248:249], v[248:249], v[234:235]
	v_mul_f32_e32 v8, v247, v45
	s_nop 0
	v_mul_f32_e32 v9, v248, v34
	s_nop 0
	v_pk_mul_f32 v[250:251], v[40:41], s[98:99] op_sel_hi:[1,0]
	v_pk_mul_f32 v[234:235], v[40:41], s[98:99] op_sel:[0,1] op_sel_hi:[1,1]
	v_exp_f32_e32 v234, v234
	v_exp_f32_e32 v235, v235
	s_nop 0
	v_pk_add_f32 v[234:235], v[234:235], s[100:101] op_sel_hi:[1,0]
	v_rcp_f32_e32 v234, v234
	v_rcp_f32_e32 v235, v235
	s_nop 0
	v_pk_mul_f32 v[250:251], v[250:251], v[234:235]
	v_mul_f32_e32 v10, v249, v35
	s_nop 0
	v_mul_f32_e32 v11, v250, v36
	s_nop 0
	v_med3_f32 v13, v6, s40, v190
	v_mov_b32_e32 v6, v163
	v_cvt_pk_fp8_f32 v6, v5, v13
	v_med3_f32 v5, v7, s40, v190
	v_med3_f32 v7, v8, s40, v190
	v_med3_f32 v8, v10, s40, v190
	v_cvt_pk_fp8_f32 v6, v5, v7 op_sel:[0,0,1]
	v_med3_f32 v5, v9, s40, v190
	v_mov_b32_e32 v7, v163
	v_cvt_pk_fp8_f32 v7, v5, v8
	v_mul_f32_e32 v12, v251, v37
	v_med3_f32 v5, v11, s40, v190
	v_med3_f32 v8, v12, s40, v190
	v_cvt_pk_fp8_f32 v7, v5, v8 op_sel:[0,0,1]
	v_ashrrev_i32_e32 v5, 31, v4
	v_lshlrev_b64 v[4:5], 7, v[4:5]
	v_lshl_add_u64 v[4:5], s[10:11], 0, v[4:5]
	v_lshl_add_u64 v[2:3], v[4:5], 0, v[2:3]
	global_store_dwordx2 v[2:3], v[6:7], off
	s_cbranch_vccz .LBB0_677
	s_waitcnt vmcnt(0)
	s_cmpk_gt_u32 s42, 0xff
	s_cbranch_scc1 .LBB0_623
	s_barrier
	s_branch .LBB0_623

.Lpeel_exit_6:
	s_mov_b32 s98, 0x3b000000
	s_mov_b32 s99, 0xbcb8aa3b
	s_mov_b32 s100, 1.0
	v_pk_mul_f32 v[236:237], v[158:159], s[98:99] op_sel_hi:[1,0]
	v_pk_mul_f32 v[234:235], v[158:159], s[98:99] op_sel:[0,1] op_sel_hi:[1,1]
	v_exp_f32_e32 v234, v234
	v_exp_f32_e32 v235, v235
	s_nop 0
	v_pk_add_f32 v[234:235], v[234:235], s[100:101] op_sel_hi:[1,0]
	v_rcp_f32_e32 v234, v234
	v_rcp_f32_e32 v235, v235
	s_nop 0
	v_pk_mul_f32 v[236:237], v[236:237], v[234:235]
	s_ashr_i32 s31, s30, 31
	s_ashr_i32 s29, s28, 31
	s_lshl_b64 s[12:13], s[30:31], 18
	s_lshl_b64 s[28:29], s[28:29], 15
	v_mov_b32_e32 v3, v195
	s_add_u32 s0, s6, s12
	v_mul_f32_e32 v5, v236, v154
	v_med3_f32 v5, v5, s40, v190
	s_nop 15
	s_nop 15
	v_mov_b32_e32 v2, v196
	v_pk_mul_f32 v[238:239], v[160:161], s[98:99] op_sel_hi:[1,0]
	v_pk_mul_f32 v[234:235], v[160:161], s[98:99] op_sel:[0,1] op_sel_hi:[1,1]
	v_exp_f32_e32 v234, v234
	v_exp_f32_e32 v235, v235
	s_nop 0
	v_pk_add_f32 v[234:235], v[234:235], s[100:101] op_sel_hi:[1,0]
	v_rcp_f32_e32 v234, v234
	v_rcp_f32_e32 v235, v235
	s_nop 0
	v_pk_mul_f32 v[238:239], v[238:239], v[234:235]
	v_mul_f32_e32 v6, v237, v155
	v_add_u32_e32 v4, s49, v3
	s_addc_u32 s1, s7, s13
	s_add_u32 s12, s0, s28
	v_mul_f32_e32 v7, v238, v156
	v_lshl_add_u32 v2, v2, 3, s50
	s_addc_u32 s13, s1, s29
	v_ashrrev_i32_e32 v3, 31, v2
	s_and_b64 vcc, exec, s[8:9]
	v_pk_mul_f32 v[240:241], v[150:151], s[98:99] op_sel_hi:[1,0]
	v_pk_mul_f32 v[234:235], v[150:151], s[98:99] op_sel:[0,1] op_sel_hi:[1,1]
	v_exp_f32_e32 v234, v234
	v_exp_f32_e32 v235, v235
	s_nop 0
	v_pk_add_f32 v[234:235], v[234:235], s[100:101] op_sel_hi:[1,0]
	v_rcp_f32_e32 v234, v234
	v_rcp_f32_e32 v235, v235
	s_nop 0
	v_pk_mul_f32 v[240:241], v[240:241], v[234:235]
	v_mul_f32_e32 v8, v239, v157
	v_mov_b32_e32 v174, v200
	v_mov_b32_e32 v172, v199
	v_mov_b32_e32 v170, v198
	v_mov_b32_e32 v168, v171
	v_mul_f32_e32 v9, v240, v146
	s_mov_b32 s28, s26
	s_mov_b32 s30, s54
	s_mov_b64 s[34:35], s[14:15]
	v_pk_mul_f32 v[242:243], v[152:153], s[98:99] op_sel_hi:[1,0]
	v_pk_mul_f32 v[234:235], v[152:153], s[98:99] op_sel:[0,1] op_sel_hi:[1,1]
	v_exp_f32_e32 v234, v234
	v_exp_f32_e32 v235, v235
	s_nop 0
	v_pk_add_f32 v[234:235], v[234:235], s[100:101] op_sel_hi:[1,0]
	v_rcp_f32_e32 v234, v234
	v_rcp_f32_e32 v235, v235
	s_nop 0
	v_pk_mul_f32 v[242:243], v[242:243], v[234:235]
	v_mul_f32_e32 v10, v241, v147
	s_nop 0
	v_mul_f32_e32 v11, v242, v148
	s_nop 0
	v_med3_f32 v13, v6, s40, v190
	v_mov_b32_e32 v6, v163
	v_cvt_pk_fp8_f32 v6, v5, v13
	v_med3_f32 v5, v7, s40, v190
	v_med3_f32 v7, v8, s40, v190
	v_med3_f32 v8, v10, s40, v190
	v_cvt_pk_fp8_f32 v6, v5, v7 op_sel:[0,0,1]
	v_med3_f32 v5, v9, s40, v190
	v_mov_b32_e32 v7, v163
	v_cvt_pk_fp8_f32 v7, v5, v8
	v_mul_f32_e32 v12, v243, v149
	v_med3_f32 v5, v11, s40, v190
	v_med3_f32 v8, v12, s40, v190
	v_cvt_pk_fp8_f32 v7, v5, v8 op_sel:[0,0,1]
	v_ashrrev_i32_e32 v5, 31, v4
	v_lshlrev_b64 v[8:9], 7, v[4:5]
	v_lshl_add_u64 v[8:9], s[12:13], 0, v[8:9]
	v_lshl_add_u64 v[8:9], v[8:9], 0, v[2:3]
	v_pk_mul_f32 v[244:245], v[142:143], s[98:99] op_sel_hi:[1,0]
	v_pk_mul_f32 v[234:235], v[142:143], s[98:99] op_sel:[0,1] op_sel_hi:[1,1]
	v_exp_f32_e32 v234, v234
	v_exp_f32_e32 v235, v235
	s_nop 0
	v_pk_add_f32 v[234:235], v[234:235], s[100:101] op_sel_hi:[1,0]
	v_rcp_f32_e32 v234, v234
	v_rcp_f32_e32 v235, v235
	s_nop 0
	v_pk_mul_f32 v[244:245], v[244:245], v[234:235]
	global_store_dwordx2 v[8:9], v[6:7], off
	s_nop 0
	s_nop 0
	v_mul_f32_e32 v5, v244, v138
	v_med3_f32 v5, v5, s40, v190
	s_nop 0
	v_mul_f32_e32 v7, v245, v139
	v_pk_mul_f32 v[246:247], v[144:145], s[98:99] op_sel_hi:[1,0]
	v_pk_mul_f32 v[234:235], v[144:145], s[98:99] op_sel:[0,1] op_sel_hi:[1,1]
	v_exp_f32_e32 v234, v234
	v_exp_f32_e32 v235, v235
	s_nop 0
	v_pk_add_f32 v[234:235], v[234:235], s[100:101] op_sel_hi:[1,0]
	v_rcp_f32_e32 v234, v234
	v_rcp_f32_e32 v235, v235
	s_nop 0
	v_pk_mul_f32 v[246:247], v[246:247], v[234:235]
	v_med3_f32 v7, v7, s40, v190
	s_nop 0
	v_mul_f32_e32 v9, v246, v140
	s_nop 0
	s_nop 0
	v_mul_f32_e32 v10, v247, v141
	v_pk_mul_f32 v[248:249], v[134:135], s[98:99] op_sel_hi:[1,0]
	v_pk_mul_f32 v[234:235], v[134:135], s[98:99] op_sel:[0,1] op_sel_hi:[1,1]
	v_exp_f32_e32 v234, v234
	v_exp_f32_e32 v235, v235
	s_nop 0
	v_pk_add_f32 v[234:235], v[234:235], s[100:101] op_sel_hi:[1,0]
	v_rcp_f32_e32 v234, v234
	v_rcp_f32_e32 v235, v235
	s_nop 0
	v_pk_mul_f32 v[248:249], v[248:249], v[234:235]
	s_nop 0
	s_nop 0
	v_mul_f32_e32 v11, v248, v130
	s_nop 0
	s_nop 0
	v_mul_f32_e32 v12, v249, v131
	v_pk_mul_f32 v[250:251], v[136:137], s[98:99] op_sel_hi:[1,0]
	v_pk_mul_f32 v[234:235], v[136:137], s[98:99] op_sel:[0,1] op_sel_hi:[1,1]
	v_exp_f32_e32 v234, v234
	v_exp_f32_e32 v235, v235
	s_nop 0
	v_pk_add_f32 v[234:235], v[234:235], s[100:101] op_sel_hi:[1,0]
	v_rcp_f32_e32 v234, v234
	v_rcp_f32_e32 v235, v235
	s_nop 0
	v_pk_mul_f32 v[250:251], v[250:251], v[234:235]
	s_nop 0
	s_nop 0
	v_mul_f32_e32 v13, v250, v132
	s_nop 0
	s_nop 0
	v_mov_b32_e32 v8, v163
	v_cvt_pk_fp8_f32 v8, v5, v7
	v_med3_f32 v5, v9, s40, v190
	v_med3_f32 v7, v10, s40, v190
	v_mov_b32_e32 v9, v163
	v_cvt_pk_fp8_f32 v8, v5, v7 op_sel:[0,0,1]
	v_med3_f32 v5, v11, s40, v190
	v_med3_f32 v7, v12, s40, v190
	v_cvt_pk_fp8_f32 v9, v5, v7
	v_mul_f32_e32 v14, v251, v133
	v_add_u32_e32 v6, 16, v4
	v_med3_f32 v5, v13, s40, v190
	v_med3_f32 v7, v14, s40, v190
	v_cvt_pk_fp8_f32 v9, v5, v7 op_sel:[0,0,1]
	v_ashrrev_i32_e32 v7, 31, v6
	v_lshlrev_b64 v[6:7], 7, v[6:7]
	v_lshl_add_u64 v[6:7], s[12:13], 0, v[6:7]
	v_lshl_add_u64 v[6:7], v[6:7], 0, v[2:3]
	v_pk_mul_f32 v[236:237], v[126:127], s[98:99] op_sel_hi:[1,0]
	v_pk_mul_f32 v[234:235], v[126:127], s[98:99] op_sel:[0,1] op_sel_hi:[1,1]
	v_exp_f32_e32 v234, v234
	v_exp_f32_e32 v235, v235
	s_nop 0
	v_pk_add_f32 v[234:235], v[234:235], s[100:101] op_sel_hi:[1,0]
	v_rcp_f32_e32 v234, v234
	v_rcp_f32_e32 v235, v235
	s_nop 0
	v_pk_mul_f32 v[236:237], v[236:237], v[234:235]
	global_store_dwordx2 v[6:7], v[8:9], off
	s_nop 0
	s_nop 0
	v_mul_f32_e32 v5, v236, v122
	v_med3_f32 v5, v5, s40, v190
	s_nop 0
	v_mul_f32_e32 v7, v237, v123
	v_pk_mul_f32 v[238:239], v[128:129], s[98:99] op_sel_hi:[1,0]
	v_pk_mul_f32 v[234:235], v[128:129], s[98:99] op_sel:[0,1] op_sel_hi:[1,1]
	v_exp_f32_e32 v234, v234
	v_exp_f32_e32 v235, v235
	s_nop 0
	v_pk_add_f32 v[234:235], v[234:235], s[100:101] op_sel_hi:[1,0]
	v_rcp_f32_e32 v234, v234
	v_rcp_f32_e32 v235, v235
	s_nop 0
	v_pk_mul_f32 v[238:239], v[238:239], v[234:235]
	v_med3_f32 v7, v7, s40, v190
	s_nop 0
	v_mul_f32_e32 v9, v238, v124
	s_nop 0
	s_nop 0
	v_mul_f32_e32 v10, v239, v125
	v_pk_mul_f32 v[240:241], v[118:119], s[98:99] op_sel_hi:[1,0]
	v_pk_mul_f32 v[234:235], v[118:119], s[98:99] op_sel:[0,1] op_sel_hi:[1,1]
	v_exp_f32_e32 v234, v234
	v_exp_f32_e32 v235, v235
	s_nop 0
	v_pk_add_f32 v[234:235], v[234:235], s[100:101] op_sel_hi:[1,0]
	v_rcp_f32_e32 v234, v234
	v_rcp_f32_e32 v235, v235
	s_nop 0
	v_pk_mul_f32 v[240:241], v[240:241], v[234:235]
	s_nop 0
	s_nop 0
	v_mul_f32_e32 v11, v240, v114
	s_nop 0
	s_nop 0
	v_mul_f32_e32 v12, v241, v115
	v_pk_mul_f32 v[242:243], v[120:121], s[98:99] op_sel_hi:[1,0]
	v_pk_mul_f32 v[234:235], v[120:121], s[98:99] op_sel:[0,1] op_sel_hi:[1,1]
	v_exp_f32_e32 v234, v234
	v_exp_f32_e32 v235, v235
	s_nop 0
	v_pk_add_f32 v[234:235], v[234:235], s[100:101] op_sel_hi:[1,0]
	v_rcp_f32_e32 v234, v234
	v_rcp_f32_e32 v235, v235
	s_nop 0
	v_pk_mul_f32 v[242:243], v[242:243], v[234:235]
	s_nop 0
	s_nop 0
	v_mul_f32_e32 v13, v242, v116
	s_nop 0
	s_nop 0
	v_mov_b32_e32 v8, v163
	v_cvt_pk_fp8_f32 v8, v5, v7
	v_med3_f32 v5, v9, s40, v190
	v_med3_f32 v7, v10, s40, v190
	v_mov_b32_e32 v9, v163
	v_cvt_pk_fp8_f32 v8, v5, v7 op_sel:[0,0,1]
	v_med3_f32 v5, v11, s40, v190
	v_med3_f32 v7, v12, s40, v190
	v_cvt_pk_fp8_f32 v9, v5, v7
	v_mul_f32_e32 v14, v243, v117
	v_add_u32_e32 v6, 32, v4
	v_med3_f32 v5, v13, s40, v190
	v_med3_f32 v7, v14, s40, v190
	v_cvt_pk_fp8_f32 v9, v5, v7 op_sel:[0,0,1]
	v_ashrrev_i32_e32 v7, 31, v6
	v_lshlrev_b64 v[6:7], 7, v[6:7]
	v_lshl_add_u64 v[6:7], s[12:13], 0, v[6:7]
	v_lshl_add_u64 v[6:7], v[6:7], 0, v[2:3]
	v_pk_mul_f32 v[244:245], v[110:111], s[98:99] op_sel_hi:[1,0]
	v_pk_mul_f32 v[234:235], v[110:111], s[98:99] op_sel:[0,1] op_sel_hi:[1,1]
	v_exp_f32_e32 v234, v234
	v_exp_f32_e32 v235, v235
	s_nop 0
	v_pk_add_f32 v[234:235], v[234:235], s[100:101] op_sel_hi:[1,0]
	v_rcp_f32_e32 v234, v234
	v_rcp_f32_e32 v235, v235
	s_nop 0
	v_pk_mul_f32 v[244:245], v[244:245], v[234:235]
	global_store_dwordx2 v[6:7], v[8:9], off
	s_nop 0
	s_nop 0
	v_mul_f32_e32 v5, v244, v106
	v_med3_f32 v5, v5, s40, v190
	s_nop 0
	v_mul_f32_e32 v7, v245, v107
	v_pk_mul_f32 v[246:247], v[112:113], s[98:99] op_sel_hi:[1,0]
	v_pk_mul_f32 v[234:235], v[112:113], s[98:99] op_sel:[0,1] op_sel_hi:[1,1]
	v_exp_f32_e32 v234, v234
	v_exp_f32_e32 v235, v235
	s_nop 0
	v_pk_add_f32 v[234:235], v[234:235], s[100:101] op_sel_hi:[1,0]
	v_rcp_f32_e32 v234, v234
	v_rcp_f32_e32 v235, v235
	s_nop 0
	v_pk_mul_f32 v[246:247], v[246:247], v[234:235]
	v_med3_f32 v7, v7, s40, v190
	s_nop 0
	v_mul_f32_e32 v9, v246, v108
	s_nop 0
	s_nop 0
	v_mul_f32_e32 v10, v247, v109
	v_pk_mul_f32 v[248:249], v[102:103], s[98:99] op_sel_hi:[1,0]
	v_pk_mul_f32 v[234:235], v[102:103], s[98:99] op_sel:[0,1] op_sel_hi:[1,1]
	v_exp_f32_e32 v234, v234
	v_exp_f32_e32 v235, v235
	s_nop 0
	v_pk_add_f32 v[234:235], v[234:235], s[100:101] op_sel_hi:[1,0]
	v_rcp_f32_e32 v234, v234
	v_rcp_f32_e32 v235, v235
	s_nop 0
	v_pk_mul_f32 v[248:249], v[248:249], v[234:235]
	s_nop 0
	s_nop 0
	v_mul_f32_e32 v11, v248, v98
	s_nop 0
	s_nop 0
	v_mul_f32_e32 v12, v249, v99
	v_pk_mul_f32 v[250:251], v[104:105], s[98:99] op_sel_hi:[1,0]
	v_pk_mul_f32 v[234:235], v[104:105], s[98:99] op_sel:[0,1] op_sel_hi:[1,1]
	v_exp_f32_e32 v234, v234
	v_exp_f32_e32 v235, v235
	s_nop 0
	v_pk_add_f32 v[234:235], v[234:235], s[100:101] op_sel_hi:[1,0]
	v_rcp_f32_e32 v234, v234
	v_rcp_f32_e32 v235, v235
	s_nop 0
	v_pk_mul_f32 v[250:251], v[250:251], v[234:235]
	s_nop 0
	s_nop 0
	v_mul_f32_e32 v13, v250, v100
	s_nop 0
	s_nop 0
	v_mov_b32_e32 v8, v163
	v_cvt_pk_fp8_f32 v8, v5, v7
	v_med3_f32 v5, v9, s40, v190
	v_med3_f32 v7, v10, s40, v190
	v_mov_b32_e32 v9, v163
	v_cvt_pk_fp8_f32 v8, v5, v7 op_sel:[0,0,1]
	v_med3_f32 v5, v11, s40, v190
	v_med3_f32 v7, v12, s40, v190
	v_cvt_pk_fp8_f32 v9, v5, v7
	v_mul_f32_e32 v14, v251, v101
	v_add_u32_e32 v6, 48, v4
	v_med3_f32 v5, v13, s40, v190
	v_med3_f32 v7, v14, s40, v190
	v_cvt_pk_fp8_f32 v9, v5, v7 op_sel:[0,0,1]
	v_ashrrev_i32_e32 v7, 31, v6
	v_lshlrev_b64 v[6:7], 7, v[6:7]
	v_lshl_add_u64 v[6:7], s[12:13], 0, v[6:7]
	v_lshl_add_u64 v[6:7], v[6:7], 0, v[2:3]
	v_pk_mul_f32 v[236:237], v[94:95], s[98:99] op_sel_hi:[1,0]
	v_pk_mul_f32 v[234:235], v[94:95], s[98:99] op_sel:[0,1] op_sel_hi:[1,1]
	v_exp_f32_e32 v234, v234
	v_exp_f32_e32 v235, v235
	s_nop 0
	v_pk_add_f32 v[234:235], v[234:235], s[100:101] op_sel_hi:[1,0]
	v_rcp_f32_e32 v234, v234
	v_rcp_f32_e32 v235, v235
	s_nop 0
	v_pk_mul_f32 v[236:237], v[236:237], v[234:235]
	global_store_dwordx2 v[6:7], v[8:9], off
	v_add_u32_e32 v6, 0x80, v4
	s_nop 0
	v_mul_f32_e32 v5, v236, v90
	v_med3_f32 v5, v5, s40, v190
	s_nop 0
	v_pk_mul_f32 v[238:239], v[96:97], s[98:99] op_sel_hi:[1,0]
	v_pk_mul_f32 v[234:235], v[96:97], s[98:99] op_sel:[0,1] op_sel_hi:[1,1]
	v_exp_f32_e32 v234, v234
	v_exp_f32_e32 v235, v235
	s_nop 0
	v_pk_add_f32 v[234:235], v[234:235], s[100:101] op_sel_hi:[1,0]
	v_rcp_f32_e32 v234, v234
	v_rcp_f32_e32 v235, v235
	s_nop 0
	v_pk_mul_f32 v[238:239], v[238:239], v[234:235]
	v_mul_f32_e32 v7, v237, v91
	v_med3_f32 v7, v7, s40, v190
	s_nop 0
	v_mul_f32_e32 v9, v238, v92
	s_nop 0
	s_nop 0
	v_mul_f32_e32 v10, v239, v93
	v_pk_mul_f32 v[240:241], v[86:87], s[98:99] op_sel_hi:[1,0]
	v_pk_mul_f32 v[234:235], v[86:87], s[98:99] op_sel:[0,1] op_sel_hi:[1,1]
	v_exp_f32_e32 v234, v234
	v_exp_f32_e32 v235, v235
	s_nop 0
	v_pk_add_f32 v[234:235], v[234:235], s[100:101] op_sel_hi:[1,0]
	v_rcp_f32_e32 v234, v234
	v_rcp_f32_e32 v235, v235
	s_nop 0
	v_pk_mul_f32 v[240:241], v[240:241], v[234:235]
	s_nop 0
	s_nop 0
	v_mul_f32_e32 v11, v240, v82
	s_nop 0
	s_nop 0
	v_mul_f32_e32 v12, v241, v83
	v_pk_mul_f32 v[242:243], v[88:89], s[98:99] op_sel_hi:[1,0]
	v_pk_mul_f32 v[234:235], v[88:89], s[98:99] op_sel:[0,1] op_sel_hi:[1,1]
	v_exp_f32_e32 v234, v234
	v_exp_f32_e32 v235, v235
	s_nop 0
	v_pk_add_f32 v[234:235], v[234:235], s[100:101] op_sel_hi:[1,0]
	v_rcp_f32_e32 v234, v234
	v_rcp_f32_e32 v235, v235
	s_nop 0
	v_pk_mul_f32 v[242:243], v[242:243], v[234:235]
	s_nop 0
	s_nop 0
	v_mul_f32_e32 v13, v242, v84
	s_nop 0
	s_nop 0
	v_mul_f32_e32 v14, v243, v85
	v_mov_b32_e32 v8, v163
	v_cvt_pk_fp8_f32 v8, v5, v7
	v_med3_f32 v5, v9, s40, v190
	v_med3_f32 v7, v10, s40, v190
	v_mov_b32_e32 v9, v163
	v_cvt_pk_fp8_f32 v8, v5, v7 op_sel:[0,0,1]
	v_med3_f32 v5, v11, s40, v190
	v_med3_f32 v7, v12, s40, v190
	v_cvt_pk_fp8_f32 v9, v5, v7
	v_med3_f32 v5, v13, s40, v190
	v_med3_f32 v7, v14, s40, v190
	v_cvt_pk_fp8_f32 v9, v5, v7 op_sel:[0,0,1]
	v_ashrrev_i32_e32 v7, 31, v6
	v_lshlrev_b64 v[6:7], 7, v[6:7]
	v_lshl_add_u64 v[6:7], s[12:13], 0, v[6:7]
	v_lshl_add_u64 v[6:7], v[6:7], 0, v[2:3]
	v_pk_mul_f32 v[244:245], v[78:79], s[98:99] op_sel_hi:[1,0]
	v_pk_mul_f32 v[234:235], v[78:79], s[98:99] op_sel:[0,1] op_sel_hi:[1,1]
	v_exp_f32_e32 v234, v234
	v_exp_f32_e32 v235, v235
	s_nop 0
	v_pk_add_f32 v[234:235], v[234:235], s[100:101] op_sel_hi:[1,0]
	v_rcp_f32_e32 v234, v234
	v_rcp_f32_e32 v235, v235
	s_nop 0
	v_pk_mul_f32 v[244:245], v[244:245], v[234:235]
	global_store_dwordx2 v[6:7], v[8:9], off
	s_nop 0
	s_nop 0
	v_mul_f32_e32 v5, v244, v74
	v_med3_f32 v5, v5, s40, v190
	s_nop 0
	v_mul_f32_e32 v7, v245, v75
	v_pk_mul_f32 v[246:247], v[80:81], s[98:99] op_sel_hi:[1,0]
	v_pk_mul_f32 v[234:235], v[80:81], s[98:99] op_sel:[0,1] op_sel_hi:[1,1]
	v_exp_f32_e32 v234, v234
	v_exp_f32_e32 v235, v235
	s_nop 0
	v_pk_add_f32 v[234:235], v[234:235], s[100:101] op_sel_hi:[1,0]
	v_rcp_f32_e32 v234, v234
	v_rcp_f32_e32 v235, v235
	s_nop 0
	v_pk_mul_f32 v[246:247], v[246:247], v[234:235]
	v_med3_f32 v7, v7, s40, v190
	s_nop 0
	v_mul_f32_e32 v9, v246, v76
	s_nop 0
	s_nop 0
	v_mul_f32_e32 v10, v247, v77
	v_pk_mul_f32 v[248:249], v[70:71], s[98:99] op_sel_hi:[1,0]
	v_pk_mul_f32 v[234:235], v[70:71], s[98:99] op_sel:[0,1] op_sel_hi:[1,1]
	v_exp_f32_e32 v234, v234
	v_exp_f32_e32 v235, v235
	s_nop 0
	v_pk_add_f32 v[234:235], v[234:235], s[100:101] op_sel_hi:[1,0]
	v_rcp_f32_e32 v234, v234
	v_rcp_f32_e32 v235, v235
	s_nop 0
	v_pk_mul_f32 v[248:249], v[248:249], v[234:235]
	s_nop 0
	s_nop 0
	v_mul_f32_e32 v11, v248, v66
	s_nop 0
	s_nop 0
	v_mul_f32_e32 v12, v249, v67
	v_pk_mul_f32 v[250:251], v[72:73], s[98:99] op_sel_hi:[1,0]
	v_pk_mul_f32 v[234:235], v[72:73], s[98:99] op_sel:[0,1] op_sel_hi:[1,1]
	v_exp_f32_e32 v234, v234
	v_exp_f32_e32 v235, v235
	s_nop 0
	v_pk_add_f32 v[234:235], v[234:235], s[100:101] op_sel_hi:[1,0]
	v_rcp_f32_e32 v234, v234
	v_rcp_f32_e32 v235, v235
	s_nop 0
	v_pk_mul_f32 v[250:251], v[250:251], v[234:235]
	s_nop 0
	s_nop 0
	v_mul_f32_e32 v13, v250, v68
	s_nop 0
	s_nop 0
	v_mov_b32_e32 v8, v163
	v_cvt_pk_fp8_f32 v8, v5, v7
	v_med3_f32 v5, v9, s40, v190
	v_med3_f32 v7, v10, s40, v190
	v_mov_b32_e32 v9, v163
	v_cvt_pk_fp8_f32 v8, v5, v7 op_sel:[0,0,1]
	v_med3_f32 v5, v11, s40, v190
	v_med3_f32 v7, v12, s40, v190
	v_cvt_pk_fp8_f32 v9, v5, v7
	v_mul_f32_e32 v14, v251, v69
	v_add_u32_e32 v6, 0x90, v4
	v_med3_f32 v5, v13, s40, v190
	v_med3_f32 v7, v14, s40, v190
	v_cvt_pk_fp8_f32 v9, v5, v7 op_sel:[0,0,1]
	v_ashrrev_i32_e32 v7, 31, v6
	v_lshlrev_b64 v[6:7], 7, v[6:7]
	v_lshl_add_u64 v[6:7], s[12:13], 0, v[6:7]
	v_lshl_add_u64 v[6:7], v[6:7], 0, v[2:3]
	v_pk_mul_f32 v[236:237], v[62:63], s[98:99] op_sel_hi:[1,0]
	v_pk_mul_f32 v[234:235], v[62:63], s[98:99] op_sel:[0,1] op_sel_hi:[1,1]
	v_exp_f32_e32 v234, v234
	v_exp_f32_e32 v235, v235
	s_nop 0
	v_pk_add_f32 v[234:235], v[234:235], s[100:101] op_sel_hi:[1,0]
	v_rcp_f32_e32 v234, v234
	v_rcp_f32_e32 v235, v235
	s_nop 0
	v_pk_mul_f32 v[236:237], v[236:237], v[234:235]
	global_store_dwordx2 v[6:7], v[8:9], off
	s_nop 0
	s_nop 0
	v_mul_f32_e32 v5, v236, v58
	v_med3_f32 v5, v5, s40, v190
	s_nop 0
	v_mul_f32_e32 v7, v237, v59
	v_pk_mul_f32 v[238:239], v[64:65], s[98:99] op_sel_hi:[1,0]
	v_pk_mul_f32 v[234:235], v[64:65], s[98:99] op_sel:[0,1] op_sel_hi:[1,1]
	v_exp_f32_e32 v234, v234
	v_exp_f32_e32 v235, v235
	s_nop 0
	v_pk_add_f32 v[234:235], v[234:235], s[100:101] op_sel_hi:[1,0]
	v_rcp_f32_e32 v234, v234
	v_rcp_f32_e32 v235, v235
	s_nop 0
	v_pk_mul_f32 v[238:239], v[238:239], v[234:235]
	v_med3_f32 v7, v7, s40, v190
	s_nop 0
	v_mul_f32_e32 v9, v238, v60
	s_nop 0
	s_nop 0
	v_mul_f32_e32 v10, v239, v61
	v_pk_mul_f32 v[240:241], v[54:55], s[98:99] op_sel_hi:[1,0]
	v_pk_mul_f32 v[234:235], v[54:55], s[98:99] op_sel:[0,1] op_sel_hi:[1,1]
	v_exp_f32_e32 v234, v234
	v_exp_f32_e32 v235, v235
	s_nop 0
	v_pk_add_f32 v[234:235], v[234:235], s[100:101] op_sel_hi:[1,0]
	v_rcp_f32_e32 v234, v234
	v_rcp_f32_e32 v235, v235
	s_nop 0
	v_pk_mul_f32 v[240:241], v[240:241], v[234:235]
	s_nop 0
	s_nop 0
	v_mul_f32_e32 v11, v240, v50
	s_nop 0
	s_nop 0
	v_mul_f32_e32 v12, v241, v51
	v_pk_mul_f32 v[242:243], v[56:57], s[98:99] op_sel_hi:[1,0]
	v_pk_mul_f32 v[234:235], v[56:57], s[98:99] op_sel:[0,1] op_sel_hi:[1,1]
	v_exp_f32_e32 v234, v234
	v_exp_f32_e32 v235, v235
	s_nop 0
	v_pk_add_f32 v[234:235], v[234:235], s[100:101] op_sel_hi:[1,0]
	v_rcp_f32_e32 v234, v234
	v_rcp_f32_e32 v235, v235
	s_nop 0
	v_pk_mul_f32 v[242:243], v[242:243], v[234:235]
	s_nop 0
	s_nop 0
	v_mul_f32_e32 v13, v242, v52
	s_nop 0
	s_nop 0
	v_mov_b32_e32 v8, v163
	v_cvt_pk_fp8_f32 v8, v5, v7
	v_med3_f32 v5, v9, s40, v190
	v_med3_f32 v7, v10, s40, v190
	v_mov_b32_e32 v9, v163
	v_cvt_pk_fp8_f32 v8, v5, v7 op_sel:[0,0,1]
	v_med3_f32 v5, v11, s40, v190
	v_med3_f32 v7, v12, s40, v190
	v_cvt_pk_fp8_f32 v9, v5, v7
	v_mul_f32_e32 v14, v243, v53
	v_add_u32_e32 v6, 0xa0, v4
	v_med3_f32 v5, v13, s40, v190
	v_med3_f32 v7, v14, s40, v190
	v_cvt_pk_fp8_f32 v9, v5, v7 op_sel:[0,0,1]
	v_ashrrev_i32_e32 v7, 31, v6
	v_lshlrev_b64 v[6:7], 7, v[6:7]
	v_lshl_add_u64 v[6:7], s[12:13], 0, v[6:7]
	v_lshl_add_u64 v[6:7], v[6:7], 0, v[2:3]
	v_pk_mul_f32 v[244:245], v[46:47], s[98:99] op_sel_hi:[1,0]
	v_pk_mul_f32 v[234:235], v[46:47], s[98:99] op_sel:[0,1] op_sel_hi:[1,1]
	v_exp_f32_e32 v234, v234
	v_exp_f32_e32 v235, v235
	s_nop 0
	v_pk_add_f32 v[234:235], v[234:235], s[100:101] op_sel_hi:[1,0]
	v_rcp_f32_e32 v234, v234
	v_rcp_f32_e32 v235, v235
	s_nop 0
	v_pk_mul_f32 v[244:245], v[244:245], v[234:235]
	global_store_dwordx2 v[6:7], v[8:9], off
	v_add_u32_e32 v4, 0xb0, v4
	s_nop 0
	v_mul_f32_e32 v5, v244, v42
	v_med3_f32 v5, v5, s40, v190
	s_nop 0
	v_pk_mul_f32 v[246:247], v[48:49], s[98:99] op_sel_hi:[1,0]
	v_pk_mul_f32 v[234:235], v[48:49], s[98:99] op_sel:[0,1] op_sel_hi:[1,1]
	v_exp_f32_e32 v234, v234
	v_exp_f32_e32 v235, v235
	s_nop 0
	v_pk_add_f32 v[234:235], v[234:235], s[100:101] op_sel_hi:[1,0]
	v_rcp_f32_e32 v234, v234
	v_rcp_f32_e32 v235, v235
	s_nop 0
	v_pk_mul_f32 v[246:247], v[246:247], v[234:235]
	v_mul_f32_e32 v6, v245, v43
	s_nop 0
	v_mul_f32_e32 v7, v246, v44
	s_nop 0
	v_pk_mul_f32 v[248:249], v[38:39], s[98:99] op_sel_hi:[1,0]
	v_pk_mul_f32 v[234:235], v[38:39], s[98:99] op_sel:[0,1] op_sel_hi:[1,1]
	v_exp_f32_e32 v234, v234
	v_exp_f32_e32 v235, v235
	s_nop 0
	v_pk_add_f32 v[234:235], v[234:235], s[100:101] op_sel_hi:[1,0]
	v_rcp_f32_e32 v234, v234
	v_rcp_f32_e32 v235, v235
	s_nop 0
	v_pk_mul_f32 v[248:249], v[248:249], v[234:235]
	v_mul_f32_e32 v8, v247, v45
	s_nop 0
	v_mul_f32_e32 v9, v248, v34
	s_nop 0
	v_pk_mul_f32 v[250:251], v[40:41], s[98:99] op_sel_hi:[1,0]
	v_pk_mul_f32 v[234:235], v[40:41], s[98:99] op_sel:[0,1] op_sel_hi:[1,1]
	v_exp_f32_e32 v234, v234
	v_exp_f32_e32 v235, v235
	s_nop 0
	v_pk_add_f32 v[234:235], v[234:235], s[100:101] op_sel_hi:[1,0]
	v_rcp_f32_e32 v234, v234
	v_rcp_f32_e32 v235, v235
	s_nop 0
	v_pk_mul_f32 v[250:251], v[250:251], v[234:235]
	v_mul_f32_e32 v10, v249, v35
	s_nop 0
	v_mul_f32_e32 v11, v250, v36
	s_nop 0
	v_med3_f32 v13, v6, s40, v190
	v_mov_b32_e32 v6, v163
	v_cvt_pk_fp8_f32 v6, v5, v13
	v_med3_f32 v5, v7, s40, v190
	v_med3_f32 v7, v8, s40, v190
	v_med3_f32 v8, v10, s40, v190
	v_cvt_pk_fp8_f32 v6, v5, v7 op_sel:[0,0,1]
	v_med3_f32 v5, v9, s40, v190
	v_mov_b32_e32 v7, v163
	v_cvt_pk_fp8_f32 v7, v5, v8
	v_mul_f32_e32 v12, v251, v37
	v_med3_f32 v5, v11, s40, v190
	v_med3_f32 v8, v12, s40, v190
	v_cvt_pk_fp8_f32 v7, v5, v8 op_sel:[0,0,1]
	v_ashrrev_i32_e32 v5, 31, v4
	v_lshlrev_b64 v[4:5], 7, v[4:5]
	v_lshl_add_u64 v[4:5], s[12:13], 0, v[4:5]
	v_lshl_add_u64 v[2:3], v[4:5], 0, v[2:3]
	global_store_dwordx2 v[2:3], v[6:7], off
	s_cbranch_vccz .LBB0_1291
	s_waitcnt vmcnt(0)
	s_cmpk_gt_u32 s42, 0xff
	s_cbranch_scc1 .LBB0_1237
	s_barrier
	s_branch .LBB0_1237

.Lpeel_exit_11:
	s_mov_b32 s98, 0x3b000000
	s_mov_b32 s99, 0xbcb8aa3b
	s_mov_b32 s100, 1.0
	v_pk_mul_f32 v[236:237], v[158:159], s[98:99] op_sel_hi:[1,0]
	v_pk_mul_f32 v[234:235], v[158:159], s[98:99] op_sel:[0,1] op_sel_hi:[1,1]
	v_exp_f32_e32 v234, v234
	v_exp_f32_e32 v235, v235
	s_nop 0
	v_pk_add_f32 v[234:235], v[234:235], s[100:101] op_sel_hi:[1,0]
	v_rcp_f32_e32 v234, v234
	v_rcp_f32_e32 v235, v235
	s_nop 0
	v_pk_mul_f32 v[236:237], v[236:237], v[234:235]
	s_ashr_i32 s35, s34, 31
	s_ashr_i32 s31, s30, 31
	s_lshl_b64 s[14:15], s[34:35], 18
	s_lshl_b64 s[30:31], s[30:31], 15
	v_mov_b32_e32 v3, v195
	s_add_u32 s0, s6, s14
	v_mul_f32_e32 v5, v236, v154
	v_med3_f32 v5, v5, s10, v190
	s_nop 15
	s_nop 15
	v_mov_b32_e32 v2, v196
	v_pk_mul_f32 v[238:239], v[160:161], s[98:99] op_sel_hi:[1,0]
	v_pk_mul_f32 v[234:235], v[160:161], s[98:99] op_sel:[0,1] op_sel_hi:[1,1]
	v_exp_f32_e32 v234, v234
	v_exp_f32_e32 v235, v235
	s_nop 0
	v_pk_add_f32 v[234:235], v[234:235], s[100:101] op_sel_hi:[1,0]
	v_rcp_f32_e32 v234, v234
	v_rcp_f32_e32 v235, v235
	s_nop 0
	v_pk_mul_f32 v[238:239], v[238:239], v[234:235]
	v_mul_f32_e32 v6, v237, v155
	v_add_u32_e32 v4, s49, v3
	s_addc_u32 s1, s7, s15
	s_add_u32 s14, s0, s30
	v_mul_f32_e32 v7, v238, v156
	v_lshl_add_u32 v2, v2, 3, s50
	s_addc_u32 s15, s1, s31
	v_ashrrev_i32_e32 v3, 31, v2
	s_and_b64 vcc, exec, s[12:13]
	v_pk_mul_f32 v[240:241], v[150:151], s[98:99] op_sel_hi:[1,0]
	v_pk_mul_f32 v[234:235], v[150:151], s[98:99] op_sel:[0,1] op_sel_hi:[1,1]
	v_exp_f32_e32 v234, v234
	v_exp_f32_e32 v235, v235
	s_nop 0
	v_pk_add_f32 v[234:235], v[234:235], s[100:101] op_sel_hi:[1,0]
	v_rcp_f32_e32 v234, v234
	v_rcp_f32_e32 v235, v235
	s_nop 0
	v_pk_mul_f32 v[240:241], v[240:241], v[234:235]
	v_mul_f32_e32 v8, v239, v157
	v_mov_b32_e32 v174, v200
	v_mov_b32_e32 v172, v199
	v_mov_b32_e32 v170, v198
	v_mov_b32_e32 v168, v171
	v_mul_f32_e32 v9, v240, v146
	s_mov_b32 s30, s28
	s_mov_b32 s34, s54
	s_mov_b64 s[36:37], s[16:17]
	v_pk_mul_f32 v[242:243], v[152:153], s[98:99] op_sel_hi:[1,0]
	v_pk_mul_f32 v[234:235], v[152:153], s[98:99] op_sel:[0,1] op_sel_hi:[1,1]
	v_exp_f32_e32 v234, v234
	v_exp_f32_e32 v235, v235
	s_nop 0
	v_pk_add_f32 v[234:235], v[234:235], s[100:101] op_sel_hi:[1,0]
	v_rcp_f32_e32 v234, v234
	v_rcp_f32_e32 v235, v235
	s_nop 0
	v_pk_mul_f32 v[242:243], v[242:243], v[234:235]
	v_mul_f32_e32 v10, v241, v147
	s_nop 0
	v_mul_f32_e32 v11, v242, v148
	s_nop 0
	v_med3_f32 v13, v6, s10, v190
	v_mov_b32_e32 v6, v163
	v_cvt_pk_fp8_f32 v6, v5, v13
	v_med3_f32 v5, v7, s10, v190
	v_med3_f32 v7, v8, s10, v190
	v_med3_f32 v8, v10, s10, v190
	v_cvt_pk_fp8_f32 v6, v5, v7 op_sel:[0,0,1]
	v_med3_f32 v5, v9, s10, v190
	v_mov_b32_e32 v7, v163
	v_cvt_pk_fp8_f32 v7, v5, v8
	v_mul_f32_e32 v12, v243, v149
	v_med3_f32 v5, v11, s10, v190
	v_med3_f32 v8, v12, s10, v190
	v_cvt_pk_fp8_f32 v7, v5, v8 op_sel:[0,0,1]
	v_ashrrev_i32_e32 v5, 31, v4
	v_lshlrev_b64 v[8:9], 7, v[4:5]
	v_lshl_add_u64 v[8:9], s[14:15], 0, v[8:9]
	v_lshl_add_u64 v[8:9], v[8:9], 0, v[2:3]
	v_pk_mul_f32 v[244:245], v[142:143], s[98:99] op_sel_hi:[1,0]
	v_pk_mul_f32 v[234:235], v[142:143], s[98:99] op_sel:[0,1] op_sel_hi:[1,1]
	v_exp_f32_e32 v234, v234
	v_exp_f32_e32 v235, v235
	s_nop 0
	v_pk_add_f32 v[234:235], v[234:235], s[100:101] op_sel_hi:[1,0]
	v_rcp_f32_e32 v234, v234
	v_rcp_f32_e32 v235, v235
	s_nop 0
	v_pk_mul_f32 v[244:245], v[244:245], v[234:235]
	global_store_dwordx2 v[8:9], v[6:7], off
	s_nop 0
	s_nop 0
	v_mul_f32_e32 v5, v244, v138
	v_med3_f32 v5, v5, s10, v190
	s_nop 0
	v_mul_f32_e32 v7, v245, v139
	v_pk_mul_f32 v[246:247], v[144:145], s[98:99] op_sel_hi:[1,0]
	v_pk_mul_f32 v[234:235], v[144:145], s[98:99] op_sel:[0,1] op_sel_hi:[1,1]
	v_exp_f32_e32 v234, v234
	v_exp_f32_e32 v235, v235
	s_nop 0
	v_pk_add_f32 v[234:235], v[234:235], s[100:101] op_sel_hi:[1,0]
	v_rcp_f32_e32 v234, v234
	v_rcp_f32_e32 v235, v235
	s_nop 0
	v_pk_mul_f32 v[246:247], v[246:247], v[234:235]
	v_med3_f32 v7, v7, s10, v190
	s_nop 0
	v_mul_f32_e32 v9, v246, v140
	s_nop 0
	s_nop 0
	v_mul_f32_e32 v10, v247, v141
	v_pk_mul_f32 v[248:249], v[134:135], s[98:99] op_sel_hi:[1,0]
	v_pk_mul_f32 v[234:235], v[134:135], s[98:99] op_sel:[0,1] op_sel_hi:[1,1]
	v_exp_f32_e32 v234, v234
	v_exp_f32_e32 v235, v235
	s_nop 0
	v_pk_add_f32 v[234:235], v[234:235], s[100:101] op_sel_hi:[1,0]
	v_rcp_f32_e32 v234, v234
	v_rcp_f32_e32 v235, v235
	s_nop 0
	v_pk_mul_f32 v[248:249], v[248:249], v[234:235]
	s_nop 0
	s_nop 0
	v_mul_f32_e32 v11, v248, v130
	s_nop 0
	s_nop 0
	v_mul_f32_e32 v12, v249, v131
	v_pk_mul_f32 v[250:251], v[136:137], s[98:99] op_sel_hi:[1,0]
	v_pk_mul_f32 v[234:235], v[136:137], s[98:99] op_sel:[0,1] op_sel_hi:[1,1]
	v_exp_f32_e32 v234, v234
	v_exp_f32_e32 v235, v235
	s_nop 0
	v_pk_add_f32 v[234:235], v[234:235], s[100:101] op_sel_hi:[1,0]
	v_rcp_f32_e32 v234, v234
	v_rcp_f32_e32 v235, v235
	s_nop 0
	v_pk_mul_f32 v[250:251], v[250:251], v[234:235]
	s_nop 0
	s_nop 0
	v_mul_f32_e32 v13, v250, v132
	s_nop 0
	s_nop 0
	v_mov_b32_e32 v8, v163
	v_cvt_pk_fp8_f32 v8, v5, v7
	v_med3_f32 v5, v9, s10, v190
	v_med3_f32 v7, v10, s10, v190
	v_mov_b32_e32 v9, v163
	v_cvt_pk_fp8_f32 v8, v5, v7 op_sel:[0,0,1]
	v_med3_f32 v5, v11, s10, v190
	v_med3_f32 v7, v12, s10, v190
	v_cvt_pk_fp8_f32 v9, v5, v7
	v_mul_f32_e32 v14, v251, v133
	v_add_u32_e32 v6, 16, v4
	v_med3_f32 v5, v13, s10, v190
	v_med3_f32 v7, v14, s10, v190
	v_cvt_pk_fp8_f32 v9, v5, v7 op_sel:[0,0,1]
	v_ashrrev_i32_e32 v7, 31, v6
	v_lshlrev_b64 v[6:7], 7, v[6:7]
	v_lshl_add_u64 v[6:7], s[14:15], 0, v[6:7]
	v_lshl_add_u64 v[6:7], v[6:7], 0, v[2:3]
	v_pk_mul_f32 v[236:237], v[126:127], s[98:99] op_sel_hi:[1,0]
	v_pk_mul_f32 v[234:235], v[126:127], s[98:99] op_sel:[0,1] op_sel_hi:[1,1]
	v_exp_f32_e32 v234, v234
	v_exp_f32_e32 v235, v235
	s_nop 0
	v_pk_add_f32 v[234:235], v[234:235], s[100:101] op_sel_hi:[1,0]
	v_rcp_f32_e32 v234, v234
	v_rcp_f32_e32 v235, v235
	s_nop 0
	v_pk_mul_f32 v[236:237], v[236:237], v[234:235]
	global_store_dwordx2 v[6:7], v[8:9], off
	s_nop 0
	s_nop 0
	v_mul_f32_e32 v5, v236, v122
	v_med3_f32 v5, v5, s10, v190
	s_nop 0
	v_mul_f32_e32 v7, v237, v123
	v_pk_mul_f32 v[238:239], v[128:129], s[98:99] op_sel_hi:[1,0]
	v_pk_mul_f32 v[234:235], v[128:129], s[98:99] op_sel:[0,1] op_sel_hi:[1,1]
	v_exp_f32_e32 v234, v234
	v_exp_f32_e32 v235, v235
	s_nop 0
	v_pk_add_f32 v[234:235], v[234:235], s[100:101] op_sel_hi:[1,0]
	v_rcp_f32_e32 v234, v234
	v_rcp_f32_e32 v235, v235
	s_nop 0
	v_pk_mul_f32 v[238:239], v[238:239], v[234:235]
	v_med3_f32 v7, v7, s10, v190
	s_nop 0
	v_mul_f32_e32 v9, v238, v124
	s_nop 0
	s_nop 0
	v_mul_f32_e32 v10, v239, v125
	v_pk_mul_f32 v[240:241], v[118:119], s[98:99] op_sel_hi:[1,0]
	v_pk_mul_f32 v[234:235], v[118:119], s[98:99] op_sel:[0,1] op_sel_hi:[1,1]
	v_exp_f32_e32 v234, v234
	v_exp_f32_e32 v235, v235
	s_nop 0
	v_pk_add_f32 v[234:235], v[234:235], s[100:101] op_sel_hi:[1,0]
	v_rcp_f32_e32 v234, v234
	v_rcp_f32_e32 v235, v235
	s_nop 0
	v_pk_mul_f32 v[240:241], v[240:241], v[234:235]
	s_nop 0
	s_nop 0
	v_mul_f32_e32 v11, v240, v114
	s_nop 0
	s_nop 0
	v_mul_f32_e32 v12, v241, v115
	v_pk_mul_f32 v[242:243], v[120:121], s[98:99] op_sel_hi:[1,0]
	v_pk_mul_f32 v[234:235], v[120:121], s[98:99] op_sel:[0,1] op_sel_hi:[1,1]
	v_exp_f32_e32 v234, v234
	v_exp_f32_e32 v235, v235
	s_nop 0
	v_pk_add_f32 v[234:235], v[234:235], s[100:101] op_sel_hi:[1,0]
	v_rcp_f32_e32 v234, v234
	v_rcp_f32_e32 v235, v235
	s_nop 0
	v_pk_mul_f32 v[242:243], v[242:243], v[234:235]
	s_nop 0
	s_nop 0
	v_mul_f32_e32 v13, v242, v116
	s_nop 0
	s_nop 0
	v_mov_b32_e32 v8, v163
	v_cvt_pk_fp8_f32 v8, v5, v7
	v_med3_f32 v5, v9, s10, v190
	v_med3_f32 v7, v10, s10, v190
	v_mov_b32_e32 v9, v163
	v_cvt_pk_fp8_f32 v8, v5, v7 op_sel:[0,0,1]
	v_med3_f32 v5, v11, s10, v190
	v_med3_f32 v7, v12, s10, v190
	v_cvt_pk_fp8_f32 v9, v5, v7
	v_mul_f32_e32 v14, v243, v117
	v_add_u32_e32 v6, 32, v4
	v_med3_f32 v5, v13, s10, v190
	v_med3_f32 v7, v14, s10, v190
	v_cvt_pk_fp8_f32 v9, v5, v7 op_sel:[0,0,1]
	v_ashrrev_i32_e32 v7, 31, v6
	v_lshlrev_b64 v[6:7], 7, v[6:7]
	v_lshl_add_u64 v[6:7], s[14:15], 0, v[6:7]
	v_lshl_add_u64 v[6:7], v[6:7], 0, v[2:3]
	v_pk_mul_f32 v[244:245], v[110:111], s[98:99] op_sel_hi:[1,0]
	v_pk_mul_f32 v[234:235], v[110:111], s[98:99] op_sel:[0,1] op_sel_hi:[1,1]
	v_exp_f32_e32 v234, v234
	v_exp_f32_e32 v235, v235
	s_nop 0
	v_pk_add_f32 v[234:235], v[234:235], s[100:101] op_sel_hi:[1,0]
	v_rcp_f32_e32 v234, v234
	v_rcp_f32_e32 v235, v235
	s_nop 0
	v_pk_mul_f32 v[244:245], v[244:245], v[234:235]
	global_store_dwordx2 v[6:7], v[8:9], off
	s_nop 0
	s_nop 0
	v_mul_f32_e32 v5, v244, v106
	v_med3_f32 v5, v5, s10, v190
	s_nop 0
	v_mul_f32_e32 v7, v245, v107
	v_pk_mul_f32 v[246:247], v[112:113], s[98:99] op_sel_hi:[1,0]
	v_pk_mul_f32 v[234:235], v[112:113], s[98:99] op_sel:[0,1] op_sel_hi:[1,1]
	v_exp_f32_e32 v234, v234
	v_exp_f32_e32 v235, v235
	s_nop 0
	v_pk_add_f32 v[234:235], v[234:235], s[100:101] op_sel_hi:[1,0]
	v_rcp_f32_e32 v234, v234
	v_rcp_f32_e32 v235, v235
	s_nop 0
	v_pk_mul_f32 v[246:247], v[246:247], v[234:235]
	v_med3_f32 v7, v7, s10, v190
	s_nop 0
	v_mul_f32_e32 v9, v246, v108
	s_nop 0
	s_nop 0
	v_mul_f32_e32 v10, v247, v109
	v_pk_mul_f32 v[248:249], v[102:103], s[98:99] op_sel_hi:[1,0]
	v_pk_mul_f32 v[234:235], v[102:103], s[98:99] op_sel:[0,1] op_sel_hi:[1,1]
	v_exp_f32_e32 v234, v234
	v_exp_f32_e32 v235, v235
	s_nop 0
	v_pk_add_f32 v[234:235], v[234:235], s[100:101] op_sel_hi:[1,0]
	v_rcp_f32_e32 v234, v234
	v_rcp_f32_e32 v235, v235
	s_nop 0
	v_pk_mul_f32 v[248:249], v[248:249], v[234:235]
	s_nop 0
	s_nop 0
	v_mul_f32_e32 v11, v248, v98
	s_nop 0
	s_nop 0
	v_mul_f32_e32 v12, v249, v99
	v_pk_mul_f32 v[250:251], v[104:105], s[98:99] op_sel_hi:[1,0]
	v_pk_mul_f32 v[234:235], v[104:105], s[98:99] op_sel:[0,1] op_sel_hi:[1,1]
	v_exp_f32_e32 v234, v234
	v_exp_f32_e32 v235, v235
	s_nop 0
	v_pk_add_f32 v[234:235], v[234:235], s[100:101] op_sel_hi:[1,0]
	v_rcp_f32_e32 v234, v234
	v_rcp_f32_e32 v235, v235
	s_nop 0
	v_pk_mul_f32 v[250:251], v[250:251], v[234:235]
	s_nop 0
	s_nop 0
	v_mul_f32_e32 v13, v250, v100
	s_nop 0
	s_nop 0
	v_mov_b32_e32 v8, v163
	v_cvt_pk_fp8_f32 v8, v5, v7
	v_med3_f32 v5, v9, s10, v190
	v_med3_f32 v7, v10, s10, v190
	v_mov_b32_e32 v9, v163
	v_cvt_pk_fp8_f32 v8, v5, v7 op_sel:[0,0,1]
	v_med3_f32 v5, v11, s10, v190
	v_med3_f32 v7, v12, s10, v190
	v_cvt_pk_fp8_f32 v9, v5, v7
	v_mul_f32_e32 v14, v251, v101
	v_add_u32_e32 v6, 48, v4
	v_med3_f32 v5, v13, s10, v190
	v_med3_f32 v7, v14, s10, v190
	v_cvt_pk_fp8_f32 v9, v5, v7 op_sel:[0,0,1]
	v_ashrrev_i32_e32 v7, 31, v6
	v_lshlrev_b64 v[6:7], 7, v[6:7]
	v_lshl_add_u64 v[6:7], s[14:15], 0, v[6:7]
	v_lshl_add_u64 v[6:7], v[6:7], 0, v[2:3]
	v_pk_mul_f32 v[236:237], v[94:95], s[98:99] op_sel_hi:[1,0]
	v_pk_mul_f32 v[234:235], v[94:95], s[98:99] op_sel:[0,1] op_sel_hi:[1,1]
	v_exp_f32_e32 v234, v234
	v_exp_f32_e32 v235, v235
	s_nop 0
	v_pk_add_f32 v[234:235], v[234:235], s[100:101] op_sel_hi:[1,0]
	v_rcp_f32_e32 v234, v234
	v_rcp_f32_e32 v235, v235
	s_nop 0
	v_pk_mul_f32 v[236:237], v[236:237], v[234:235]
	global_store_dwordx2 v[6:7], v[8:9], off
	v_add_u32_e32 v6, 0x80, v4
	s_nop 0
	v_mul_f32_e32 v5, v236, v90
	v_med3_f32 v5, v5, s10, v190
	s_nop 0
	v_pk_mul_f32 v[238:239], v[96:97], s[98:99] op_sel_hi:[1,0]
	v_pk_mul_f32 v[234:235], v[96:97], s[98:99] op_sel:[0,1] op_sel_hi:[1,1]
	v_exp_f32_e32 v234, v234
	v_exp_f32_e32 v235, v235
	s_nop 0
	v_pk_add_f32 v[234:235], v[234:235], s[100:101] op_sel_hi:[1,0]
	v_rcp_f32_e32 v234, v234
	v_rcp_f32_e32 v235, v235
	s_nop 0
	v_pk_mul_f32 v[238:239], v[238:239], v[234:235]
	v_mul_f32_e32 v7, v237, v91
	v_med3_f32 v7, v7, s10, v190
	s_nop 0
	v_mul_f32_e32 v9, v238, v92
	s_nop 0
	s_nop 0
	v_mul_f32_e32 v10, v239, v93
	v_pk_mul_f32 v[240:241], v[86:87], s[98:99] op_sel_hi:[1,0]
	v_pk_mul_f32 v[234:235], v[86:87], s[98:99] op_sel:[0,1] op_sel_hi:[1,1]
	v_exp_f32_e32 v234, v234
	v_exp_f32_e32 v235, v235
	s_nop 0
	v_pk_add_f32 v[234:235], v[234:235], s[100:101] op_sel_hi:[1,0]
	v_rcp_f32_e32 v234, v234
	v_rcp_f32_e32 v235, v235
	s_nop 0
	v_pk_mul_f32 v[240:241], v[240:241], v[234:235]
	s_nop 0
	s_nop 0
	v_mul_f32_e32 v11, v240, v82
	s_nop 0
	s_nop 0
	v_mul_f32_e32 v12, v241, v83
	v_pk_mul_f32 v[242:243], v[88:89], s[98:99] op_sel_hi:[1,0]
	v_pk_mul_f32 v[234:235], v[88:89], s[98:99] op_sel:[0,1] op_sel_hi:[1,1]
	v_exp_f32_e32 v234, v234
	v_exp_f32_e32 v235, v235
	s_nop 0
	v_pk_add_f32 v[234:235], v[234:235], s[100:101] op_sel_hi:[1,0]
	v_rcp_f32_e32 v234, v234
	v_rcp_f32_e32 v235, v235
	s_nop 0
	v_pk_mul_f32 v[242:243], v[242:243], v[234:235]
	s_nop 0
	s_nop 0
	v_mul_f32_e32 v13, v242, v84
	s_nop 0
	s_nop 0
	v_mul_f32_e32 v14, v243, v85
	v_mov_b32_e32 v8, v163
	v_cvt_pk_fp8_f32 v8, v5, v7
	v_med3_f32 v5, v9, s10, v190
	v_med3_f32 v7, v10, s10, v190
	v_mov_b32_e32 v9, v163
	v_cvt_pk_fp8_f32 v8, v5, v7 op_sel:[0,0,1]
	v_med3_f32 v5, v11, s10, v190
	v_med3_f32 v7, v12, s10, v190
	v_cvt_pk_fp8_f32 v9, v5, v7
	v_med3_f32 v5, v13, s10, v190
	v_med3_f32 v7, v14, s10, v190
	v_cvt_pk_fp8_f32 v9, v5, v7 op_sel:[0,0,1]
	v_ashrrev_i32_e32 v7, 31, v6
	v_lshlrev_b64 v[6:7], 7, v[6:7]
	v_lshl_add_u64 v[6:7], s[14:15], 0, v[6:7]
	v_lshl_add_u64 v[6:7], v[6:7], 0, v[2:3]
	v_pk_mul_f32 v[244:245], v[78:79], s[98:99] op_sel_hi:[1,0]
	v_pk_mul_f32 v[234:235], v[78:79], s[98:99] op_sel:[0,1] op_sel_hi:[1,1]
	v_exp_f32_e32 v234, v234
	v_exp_f32_e32 v235, v235
	s_nop 0
	v_pk_add_f32 v[234:235], v[234:235], s[100:101] op_sel_hi:[1,0]
	v_rcp_f32_e32 v234, v234
	v_rcp_f32_e32 v235, v235
	s_nop 0
	v_pk_mul_f32 v[244:245], v[244:245], v[234:235]
	global_store_dwordx2 v[6:7], v[8:9], off
	s_nop 0
	s_nop 0
	v_mul_f32_e32 v5, v244, v74
	v_med3_f32 v5, v5, s10, v190
	s_nop 0
	v_mul_f32_e32 v7, v245, v75
	v_pk_mul_f32 v[246:247], v[80:81], s[98:99] op_sel_hi:[1,0]
	v_pk_mul_f32 v[234:235], v[80:81], s[98:99] op_sel:[0,1] op_sel_hi:[1,1]
	v_exp_f32_e32 v234, v234
	v_exp_f32_e32 v235, v235
	s_nop 0
	v_pk_add_f32 v[234:235], v[234:235], s[100:101] op_sel_hi:[1,0]
	v_rcp_f32_e32 v234, v234
	v_rcp_f32_e32 v235, v235
	s_nop 0
	v_pk_mul_f32 v[246:247], v[246:247], v[234:235]
	v_med3_f32 v7, v7, s10, v190
	s_nop 0
	v_mul_f32_e32 v9, v246, v76
	s_nop 0
	s_nop 0
	v_mul_f32_e32 v10, v247, v77
	v_pk_mul_f32 v[248:249], v[70:71], s[98:99] op_sel_hi:[1,0]
	v_pk_mul_f32 v[234:235], v[70:71], s[98:99] op_sel:[0,1] op_sel_hi:[1,1]
	v_exp_f32_e32 v234, v234
	v_exp_f32_e32 v235, v235
	s_nop 0
	v_pk_add_f32 v[234:235], v[234:235], s[100:101] op_sel_hi:[1,0]
	v_rcp_f32_e32 v234, v234
	v_rcp_f32_e32 v235, v235
	s_nop 0
	v_pk_mul_f32 v[248:249], v[248:249], v[234:235]
	s_nop 0
	s_nop 0
	v_mul_f32_e32 v11, v248, v66
	s_nop 0
	s_nop 0
	v_mul_f32_e32 v12, v249, v67
	v_pk_mul_f32 v[250:251], v[72:73], s[98:99] op_sel_hi:[1,0]
	v_pk_mul_f32 v[234:235], v[72:73], s[98:99] op_sel:[0,1] op_sel_hi:[1,1]
	v_exp_f32_e32 v234, v234
	v_exp_f32_e32 v235, v235
	s_nop 0
	v_pk_add_f32 v[234:235], v[234:235], s[100:101] op_sel_hi:[1,0]
	v_rcp_f32_e32 v234, v234
	v_rcp_f32_e32 v235, v235
	s_nop 0
	v_pk_mul_f32 v[250:251], v[250:251], v[234:235]
	s_nop 0
	s_nop 0
	v_mul_f32_e32 v13, v250, v68
	s_nop 0
	s_nop 0
	v_mov_b32_e32 v8, v163
	v_cvt_pk_fp8_f32 v8, v5, v7
	v_med3_f32 v5, v9, s10, v190
	v_med3_f32 v7, v10, s10, v190
	v_mov_b32_e32 v9, v163
	v_cvt_pk_fp8_f32 v8, v5, v7 op_sel:[0,0,1]
	v_med3_f32 v5, v11, s10, v190
	v_med3_f32 v7, v12, s10, v190
	v_cvt_pk_fp8_f32 v9, v5, v7
	v_mul_f32_e32 v14, v251, v69
	v_add_u32_e32 v6, 0x90, v4
	v_med3_f32 v5, v13, s10, v190
	v_med3_f32 v7, v14, s10, v190
	v_cvt_pk_fp8_f32 v9, v5, v7 op_sel:[0,0,1]
	v_ashrrev_i32_e32 v7, 31, v6
	v_lshlrev_b64 v[6:7], 7, v[6:7]
	v_lshl_add_u64 v[6:7], s[14:15], 0, v[6:7]
	v_lshl_add_u64 v[6:7], v[6:7], 0, v[2:3]
	v_pk_mul_f32 v[236:237], v[62:63], s[98:99] op_sel_hi:[1,0]
	v_pk_mul_f32 v[234:235], v[62:63], s[98:99] op_sel:[0,1] op_sel_hi:[1,1]
	v_exp_f32_e32 v234, v234
	v_exp_f32_e32 v235, v235
	s_nop 0
	v_pk_add_f32 v[234:235], v[234:235], s[100:101] op_sel_hi:[1,0]
	v_rcp_f32_e32 v234, v234
	v_rcp_f32_e32 v235, v235
	s_nop 0
	v_pk_mul_f32 v[236:237], v[236:237], v[234:235]
	global_store_dwordx2 v[6:7], v[8:9], off
	s_nop 0
	s_nop 0
	v_mul_f32_e32 v5, v236, v58
	v_med3_f32 v5, v5, s10, v190
	s_nop 0
	v_mul_f32_e32 v7, v237, v59
	v_pk_mul_f32 v[238:239], v[64:65], s[98:99] op_sel_hi:[1,0]
	v_pk_mul_f32 v[234:235], v[64:65], s[98:99] op_sel:[0,1] op_sel_hi:[1,1]
	v_exp_f32_e32 v234, v234
	v_exp_f32_e32 v235, v235
	s_nop 0
	v_pk_add_f32 v[234:235], v[234:235], s[100:101] op_sel_hi:[1,0]
	v_rcp_f32_e32 v234, v234
	v_rcp_f32_e32 v235, v235
	s_nop 0
	v_pk_mul_f32 v[238:239], v[238:239], v[234:235]
	v_med3_f32 v7, v7, s10, v190
	s_nop 0
	v_mul_f32_e32 v9, v238, v60
	s_nop 0
	s_nop 0
	v_mul_f32_e32 v10, v239, v61
	v_pk_mul_f32 v[240:241], v[54:55], s[98:99] op_sel_hi:[1,0]
	v_pk_mul_f32 v[234:235], v[54:55], s[98:99] op_sel:[0,1] op_sel_hi:[1,1]
	v_exp_f32_e32 v234, v234
	v_exp_f32_e32 v235, v235
	s_nop 0
	v_pk_add_f32 v[234:235], v[234:235], s[100:101] op_sel_hi:[1,0]
	v_rcp_f32_e32 v234, v234
	v_rcp_f32_e32 v235, v235
	s_nop 0
	v_pk_mul_f32 v[240:241], v[240:241], v[234:235]
	s_nop 0
	s_nop 0
	v_mul_f32_e32 v11, v240, v50
	s_nop 0
	s_nop 0
	v_mul_f32_e32 v12, v241, v51
	v_pk_mul_f32 v[242:243], v[56:57], s[98:99] op_sel_hi:[1,0]
	v_pk_mul_f32 v[234:235], v[56:57], s[98:99] op_sel:[0,1] op_sel_hi:[1,1]
	v_exp_f32_e32 v234, v234
	v_exp_f32_e32 v235, v235
	s_nop 0
	v_pk_add_f32 v[234:235], v[234:235], s[100:101] op_sel_hi:[1,0]
	v_rcp_f32_e32 v234, v234
	v_rcp_f32_e32 v235, v235
	s_nop 0
	v_pk_mul_f32 v[242:243], v[242:243], v[234:235]
	s_nop 0
	s_nop 0
	v_mul_f32_e32 v13, v242, v52
	s_nop 0
	s_nop 0
	v_mov_b32_e32 v8, v163
	v_cvt_pk_fp8_f32 v8, v5, v7
	v_med3_f32 v5, v9, s10, v190
	v_med3_f32 v7, v10, s10, v190
	v_mov_b32_e32 v9, v163
	v_cvt_pk_fp8_f32 v8, v5, v7 op_sel:[0,0,1]
	v_med3_f32 v5, v11, s10, v190
	v_med3_f32 v7, v12, s10, v190
	v_cvt_pk_fp8_f32 v9, v5, v7
	v_mul_f32_e32 v14, v243, v53
	v_add_u32_e32 v6, 0xa0, v4
	v_med3_f32 v5, v13, s10, v190
	v_med3_f32 v7, v14, s10, v190
	v_cvt_pk_fp8_f32 v9, v5, v7 op_sel:[0,0,1]
	v_ashrrev_i32_e32 v7, 31, v6
	v_lshlrev_b64 v[6:7], 7, v[6:7]
	v_lshl_add_u64 v[6:7], s[14:15], 0, v[6:7]
	v_lshl_add_u64 v[6:7], v[6:7], 0, v[2:3]
	v_pk_mul_f32 v[244:245], v[46:47], s[98:99] op_sel_hi:[1,0]
	v_pk_mul_f32 v[234:235], v[46:47], s[98:99] op_sel:[0,1] op_sel_hi:[1,1]
	v_exp_f32_e32 v234, v234
	v_exp_f32_e32 v235, v235
	s_nop 0
	v_pk_add_f32 v[234:235], v[234:235], s[100:101] op_sel_hi:[1,0]
	v_rcp_f32_e32 v234, v234
	v_rcp_f32_e32 v235, v235
	s_nop 0
	v_pk_mul_f32 v[244:245], v[244:245], v[234:235]
	global_store_dwordx2 v[6:7], v[8:9], off
	v_add_u32_e32 v4, 0xb0, v4
	s_nop 0
	v_mul_f32_e32 v5, v244, v42
	v_med3_f32 v5, v5, s10, v190
	s_nop 0
	v_pk_mul_f32 v[246:247], v[48:49], s[98:99] op_sel_hi:[1,0]
	v_pk_mul_f32 v[234:235], v[48:49], s[98:99] op_sel:[0,1] op_sel_hi:[1,1]
	v_exp_f32_e32 v234, v234
	v_exp_f32_e32 v235, v235
	s_nop 0
	v_pk_add_f32 v[234:235], v[234:235], s[100:101] op_sel_hi:[1,0]
	v_rcp_f32_e32 v234, v234
	v_rcp_f32_e32 v235, v235
	s_nop 0
	v_pk_mul_f32 v[246:247], v[246:247], v[234:235]
	v_mul_f32_e32 v6, v245, v43
	s_nop 0
	v_mul_f32_e32 v7, v246, v44
	s_nop 0
	v_pk_mul_f32 v[248:249], v[38:39], s[98:99] op_sel_hi:[1,0]
	v_pk_mul_f32 v[234:235], v[38:39], s[98:99] op_sel:[0,1] op_sel_hi:[1,1]
	v_exp_f32_e32 v234, v234
	v_exp_f32_e32 v235, v235
	s_nop 0
	v_pk_add_f32 v[234:235], v[234:235], s[100:101] op_sel_hi:[1,0]
	v_rcp_f32_e32 v234, v234
	v_rcp_f32_e32 v235, v235
	s_nop 0
	v_pk_mul_f32 v[248:249], v[248:249], v[234:235]
	v_mul_f32_e32 v8, v247, v45
	s_nop 0
	v_mul_f32_e32 v9, v248, v34
	s_nop 0
	v_pk_mul_f32 v[250:251], v[40:41], s[98:99] op_sel_hi:[1,0]
	v_pk_mul_f32 v[234:235], v[40:41], s[98:99] op_sel:[0,1] op_sel_hi:[1,1]
	v_exp_f32_e32 v234, v234
	v_exp_f32_e32 v235, v235
	s_nop 0
	v_pk_add_f32 v[234:235], v[234:235], s[100:101] op_sel_hi:[1,0]
	v_rcp_f32_e32 v234, v234
	v_rcp_f32_e32 v235, v235
	s_nop 0
	v_pk_mul_f32 v[250:251], v[250:251], v[234:235]
	v_mul_f32_e32 v10, v249, v35
	s_nop 0
	v_mul_f32_e32 v11, v250, v36
	s_nop 0
	v_med3_f32 v13, v6, s10, v190
	v_mov_b32_e32 v6, v163
	v_cvt_pk_fp8_f32 v6, v5, v13
	v_med3_f32 v5, v7, s10, v190
	v_med3_f32 v7, v8, s10, v190
	v_med3_f32 v8, v10, s10, v190
	v_cvt_pk_fp8_f32 v6, v5, v7 op_sel:[0,0,1]
	v_med3_f32 v5, v9, s10, v190
	v_mov_b32_e32 v7, v163
	v_cvt_pk_fp8_f32 v7, v5, v8
	v_mul_f32_e32 v12, v251, v37
	v_med3_f32 v5, v11, s10, v190
	v_med3_f32 v8, v12, s10, v190
	v_cvt_pk_fp8_f32 v7, v5, v8 op_sel:[0,0,1]
	v_ashrrev_i32_e32 v5, 31, v4
	v_lshlrev_b64 v[4:5], 7, v[4:5]
	v_lshl_add_u64 v[4:5], s[14:15], 0, v[4:5]
	v_lshl_add_u64 v[2:3], v[4:5], 0, v[2:3]
	global_store_dwordx2 v[2:3], v[6:7], off
	s_cbranch_vccz .LBB0_2030
	s_waitcnt vmcnt(0)
	s_cmpk_gt_u32 s42, 0xff
	s_cbranch_scc1 .LBB0_1976
	s_barrier
	s_branch .LBB0_1976

.Lpeel_exit_17:
	s_mov_b32 s98, 0x3b000000
	s_mov_b32 s99, 0xbcb8aa3b
	s_mov_b32 s100, 1.0
	v_pk_mul_f32 v[236:237], v[158:159], s[98:99] op_sel_hi:[1,0]
	v_pk_mul_f32 v[234:235], v[158:159], s[98:99] op_sel:[0,1] op_sel_hi:[1,1]
	v_exp_f32_e32 v234, v234
	v_exp_f32_e32 v235, v235
	s_nop 0
	v_pk_add_f32 v[234:235], v[234:235], s[100:101] op_sel_hi:[1,0]
	v_rcp_f32_e32 v234, v234
	v_rcp_f32_e32 v235, v235
	s_nop 0
	v_pk_mul_f32 v[236:237], v[236:237], v[234:235]
	s_ashr_i32 s29, s28, 31
	s_ashr_i32 s27, s26, 31
	s_lshl_b64 s[10:11], s[28:29], 18
	s_lshl_b64 s[26:27], s[26:27], 15
	v_mov_b32_e32 v3, v194
	s_add_u32 s0, s8, s10
	v_mul_f32_e32 v5, v236, v154
	v_med3_f32 v5, v5, s40, v189
	s_nop 15
	s_nop 15
	v_mov_b32_e32 v2, v195
	v_pk_mul_f32 v[238:239], v[160:161], s[98:99] op_sel_hi:[1,0]
	v_pk_mul_f32 v[234:235], v[160:161], s[98:99] op_sel:[0,1] op_sel_hi:[1,1]
	v_exp_f32_e32 v234, v234
	v_exp_f32_e32 v235, v235
	s_nop 0
	v_pk_add_f32 v[234:235], v[234:235], s[100:101] op_sel_hi:[1,0]
	v_rcp_f32_e32 v234, v234
	v_rcp_f32_e32 v235, v235
	s_nop 0
	v_pk_mul_f32 v[238:239], v[238:239], v[234:235]
	v_mul_f32_e32 v6, v237, v155
	v_add_u32_e32 v4, s49, v3
	s_addc_u32 s1, s9, s11
	s_add_u32 s10, s0, s26
	v_mul_f32_e32 v7, v238, v156
	v_lshl_add_u32 v2, v2, 3, s50
	s_addc_u32 s11, s1, s27
	v_ashrrev_i32_e32 v3, 31, v2
	s_and_b64 vcc, exec, s[6:7]
	v_pk_mul_f32 v[240:241], v[150:151], s[98:99] op_sel_hi:[1,0]
	v_pk_mul_f32 v[234:235], v[150:151], s[98:99] op_sel:[0,1] op_sel_hi:[1,1]
	v_exp_f32_e32 v234, v234
	v_exp_f32_e32 v235, v235
	s_nop 0
	v_pk_add_f32 v[234:235], v[234:235], s[100:101] op_sel_hi:[1,0]
	v_rcp_f32_e32 v234, v234
	v_rcp_f32_e32 v235, v235
	s_nop 0
	v_pk_mul_f32 v[240:241], v[240:241], v[234:235]
	v_mul_f32_e32 v8, v239, v157
	v_mov_b32_e32 v174, v199
	v_mov_b32_e32 v172, v198
	v_mov_b32_e32 v170, v197
	v_mov_b32_e32 v168, v171
	v_mul_f32_e32 v9, v240, v146
	s_mov_b32 s26, s24
	s_mov_b32 s28, s54
	s_mov_b64 s[30:31], s[12:13]
	v_pk_mul_f32 v[242:243], v[152:153], s[98:99] op_sel_hi:[1,0]
	v_pk_mul_f32 v[234:235], v[152:153], s[98:99] op_sel:[0,1] op_sel_hi:[1,1]
	v_exp_f32_e32 v234, v234
	v_exp_f32_e32 v235, v235
	s_nop 0
	v_pk_add_f32 v[234:235], v[234:235], s[100:101] op_sel_hi:[1,0]
	v_rcp_f32_e32 v234, v234
	v_rcp_f32_e32 v235, v235
	s_nop 0
	v_pk_mul_f32 v[242:243], v[242:243], v[234:235]
	v_mul_f32_e32 v10, v241, v147
	s_nop 0
	v_mul_f32_e32 v11, v242, v148
	s_nop 0
	v_med3_f32 v13, v6, s40, v189
	v_mov_b32_e32 v6, v163
	v_cvt_pk_fp8_f32 v6, v5, v13
	v_med3_f32 v5, v7, s40, v189
	v_med3_f32 v7, v8, s40, v189
	v_med3_f32 v8, v10, s40, v189
	v_cvt_pk_fp8_f32 v6, v5, v7 op_sel:[0,0,1]
	v_med3_f32 v5, v9, s40, v189
	v_mov_b32_e32 v7, v163
	v_cvt_pk_fp8_f32 v7, v5, v8
	v_mul_f32_e32 v12, v243, v149
	v_med3_f32 v5, v11, s40, v189
	v_med3_f32 v8, v12, s40, v189
	v_cvt_pk_fp8_f32 v7, v5, v8 op_sel:[0,0,1]
	v_ashrrev_i32_e32 v5, 31, v4
	v_lshlrev_b64 v[8:9], 7, v[4:5]
	v_lshl_add_u64 v[8:9], s[10:11], 0, v[8:9]
	v_lshl_add_u64 v[8:9], v[8:9], 0, v[2:3]
	v_pk_mul_f32 v[244:245], v[142:143], s[98:99] op_sel_hi:[1,0]
	v_pk_mul_f32 v[234:235], v[142:143], s[98:99] op_sel:[0,1] op_sel_hi:[1,1]
	v_exp_f32_e32 v234, v234
	v_exp_f32_e32 v235, v235
	s_nop 0
	v_pk_add_f32 v[234:235], v[234:235], s[100:101] op_sel_hi:[1,0]
	v_rcp_f32_e32 v234, v234
	v_rcp_f32_e32 v235, v235
	s_nop 0
	v_pk_mul_f32 v[244:245], v[244:245], v[234:235]
	global_store_dwordx2 v[8:9], v[6:7], off
	s_nop 0
	s_nop 0
	v_mul_f32_e32 v5, v244, v138
	v_med3_f32 v5, v5, s40, v189
	s_nop 0
	v_mul_f32_e32 v7, v245, v139
	v_pk_mul_f32 v[246:247], v[144:145], s[98:99] op_sel_hi:[1,0]
	v_pk_mul_f32 v[234:235], v[144:145], s[98:99] op_sel:[0,1] op_sel_hi:[1,1]
	v_exp_f32_e32 v234, v234
	v_exp_f32_e32 v235, v235
	s_nop 0
	v_pk_add_f32 v[234:235], v[234:235], s[100:101] op_sel_hi:[1,0]
	v_rcp_f32_e32 v234, v234
	v_rcp_f32_e32 v235, v235
	s_nop 0
	v_pk_mul_f32 v[246:247], v[246:247], v[234:235]
	v_med3_f32 v7, v7, s40, v189
	s_nop 0
	v_mul_f32_e32 v9, v246, v140
	s_nop 0
	s_nop 0
	v_mul_f32_e32 v10, v247, v141
	v_pk_mul_f32 v[248:249], v[134:135], s[98:99] op_sel_hi:[1,0]
	v_pk_mul_f32 v[234:235], v[134:135], s[98:99] op_sel:[0,1] op_sel_hi:[1,1]
	v_exp_f32_e32 v234, v234
	v_exp_f32_e32 v235, v235
	s_nop 0
	v_pk_add_f32 v[234:235], v[234:235], s[100:101] op_sel_hi:[1,0]
	v_rcp_f32_e32 v234, v234
	v_rcp_f32_e32 v235, v235
	s_nop 0
	v_pk_mul_f32 v[248:249], v[248:249], v[234:235]
	s_nop 0
	s_nop 0
	v_mul_f32_e32 v11, v248, v130
	s_nop 0
	s_nop 0
	v_mul_f32_e32 v12, v249, v131
	v_pk_mul_f32 v[250:251], v[136:137], s[98:99] op_sel_hi:[1,0]
	v_pk_mul_f32 v[234:235], v[136:137], s[98:99] op_sel:[0,1] op_sel_hi:[1,1]
	v_exp_f32_e32 v234, v234
	v_exp_f32_e32 v235, v235
	s_nop 0
	v_pk_add_f32 v[234:235], v[234:235], s[100:101] op_sel_hi:[1,0]
	v_rcp_f32_e32 v234, v234
	v_rcp_f32_e32 v235, v235
	s_nop 0
	v_pk_mul_f32 v[250:251], v[250:251], v[234:235]
	s_nop 0
	s_nop 0
	v_mul_f32_e32 v13, v250, v132
	s_nop 0
	s_nop 0
	v_mov_b32_e32 v8, v163
	v_cvt_pk_fp8_f32 v8, v5, v7
	v_med3_f32 v5, v9, s40, v189
	v_med3_f32 v7, v10, s40, v189
	v_mov_b32_e32 v9, v163
	v_cvt_pk_fp8_f32 v8, v5, v7 op_sel:[0,0,1]
	v_med3_f32 v5, v11, s40, v189
	v_med3_f32 v7, v12, s40, v189
	v_cvt_pk_fp8_f32 v9, v5, v7
	v_mul_f32_e32 v14, v251, v133
	v_add_u32_e32 v6, 16, v4
	v_med3_f32 v5, v13, s40, v189
	v_med3_f32 v7, v14, s40, v189
	v_cvt_pk_fp8_f32 v9, v5, v7 op_sel:[0,0,1]
	v_ashrrev_i32_e32 v7, 31, v6
	v_lshlrev_b64 v[6:7], 7, v[6:7]
	v_lshl_add_u64 v[6:7], s[10:11], 0, v[6:7]
	v_lshl_add_u64 v[6:7], v[6:7], 0, v[2:3]
	v_pk_mul_f32 v[236:237], v[126:127], s[98:99] op_sel_hi:[1,0]
	v_pk_mul_f32 v[234:235], v[126:127], s[98:99] op_sel:[0,1] op_sel_hi:[1,1]
	v_exp_f32_e32 v234, v234
	v_exp_f32_e32 v235, v235
	s_nop 0
	v_pk_add_f32 v[234:235], v[234:235], s[100:101] op_sel_hi:[1,0]
	v_rcp_f32_e32 v234, v234
	v_rcp_f32_e32 v235, v235
	s_nop 0
	v_pk_mul_f32 v[236:237], v[236:237], v[234:235]
	global_store_dwordx2 v[6:7], v[8:9], off
	s_nop 0
	s_nop 0
	v_mul_f32_e32 v5, v236, v122
	v_med3_f32 v5, v5, s40, v189
	s_nop 0
	v_mul_f32_e32 v7, v237, v123
	v_pk_mul_f32 v[238:239], v[128:129], s[98:99] op_sel_hi:[1,0]
	v_pk_mul_f32 v[234:235], v[128:129], s[98:99] op_sel:[0,1] op_sel_hi:[1,1]
	v_exp_f32_e32 v234, v234
	v_exp_f32_e32 v235, v235
	s_nop 0
	v_pk_add_f32 v[234:235], v[234:235], s[100:101] op_sel_hi:[1,0]
	v_rcp_f32_e32 v234, v234
	v_rcp_f32_e32 v235, v235
	s_nop 0
	v_pk_mul_f32 v[238:239], v[238:239], v[234:235]
	v_med3_f32 v7, v7, s40, v189
	s_nop 0
	v_mul_f32_e32 v9, v238, v124
	s_nop 0
	s_nop 0
	v_mul_f32_e32 v10, v239, v125
	v_pk_mul_f32 v[240:241], v[118:119], s[98:99] op_sel_hi:[1,0]
	v_pk_mul_f32 v[234:235], v[118:119], s[98:99] op_sel:[0,1] op_sel_hi:[1,1]
	v_exp_f32_e32 v234, v234
	v_exp_f32_e32 v235, v235
	s_nop 0
	v_pk_add_f32 v[234:235], v[234:235], s[100:101] op_sel_hi:[1,0]
	v_rcp_f32_e32 v234, v234
	v_rcp_f32_e32 v235, v235
	s_nop 0
	v_pk_mul_f32 v[240:241], v[240:241], v[234:235]
	s_nop 0
	s_nop 0
	v_mul_f32_e32 v11, v240, v114
	s_nop 0
	s_nop 0
	v_mul_f32_e32 v12, v241, v115
	v_pk_mul_f32 v[242:243], v[120:121], s[98:99] op_sel_hi:[1,0]
	v_pk_mul_f32 v[234:235], v[120:121], s[98:99] op_sel:[0,1] op_sel_hi:[1,1]
	v_exp_f32_e32 v234, v234
	v_exp_f32_e32 v235, v235
	s_nop 0
	v_pk_add_f32 v[234:235], v[234:235], s[100:101] op_sel_hi:[1,0]
	v_rcp_f32_e32 v234, v234
	v_rcp_f32_e32 v235, v235
	s_nop 0
	v_pk_mul_f32 v[242:243], v[242:243], v[234:235]
	s_nop 0
	s_nop 0
	v_mul_f32_e32 v13, v242, v116
	s_nop 0
	s_nop 0
	v_mov_b32_e32 v8, v163
	v_cvt_pk_fp8_f32 v8, v5, v7
	v_med3_f32 v5, v9, s40, v189
	v_med3_f32 v7, v10, s40, v189
	v_mov_b32_e32 v9, v163
	v_cvt_pk_fp8_f32 v8, v5, v7 op_sel:[0,0,1]
	v_med3_f32 v5, v11, s40, v189
	v_med3_f32 v7, v12, s40, v189
	v_cvt_pk_fp8_f32 v9, v5, v7
	v_mul_f32_e32 v14, v243, v117
	v_add_u32_e32 v6, 32, v4
	v_med3_f32 v5, v13, s40, v189
	v_med3_f32 v7, v14, s40, v189
	v_cvt_pk_fp8_f32 v9, v5, v7 op_sel:[0,0,1]
	v_ashrrev_i32_e32 v7, 31, v6
	v_lshlrev_b64 v[6:7], 7, v[6:7]
	v_lshl_add_u64 v[6:7], s[10:11], 0, v[6:7]
	v_lshl_add_u64 v[6:7], v[6:7], 0, v[2:3]
	v_pk_mul_f32 v[244:245], v[110:111], s[98:99] op_sel_hi:[1,0]
	v_pk_mul_f32 v[234:235], v[110:111], s[98:99] op_sel:[0,1] op_sel_hi:[1,1]
	v_exp_f32_e32 v234, v234
	v_exp_f32_e32 v235, v235
	s_nop 0
	v_pk_add_f32 v[234:235], v[234:235], s[100:101] op_sel_hi:[1,0]
	v_rcp_f32_e32 v234, v234
	v_rcp_f32_e32 v235, v235
	s_nop 0
	v_pk_mul_f32 v[244:245], v[244:245], v[234:235]
	global_store_dwordx2 v[6:7], v[8:9], off
	s_nop 0
	s_nop 0
	v_mul_f32_e32 v5, v244, v106
	v_med3_f32 v5, v5, s40, v189
	s_nop 0
	v_mul_f32_e32 v7, v245, v107
	v_pk_mul_f32 v[246:247], v[112:113], s[98:99] op_sel_hi:[1,0]
	v_pk_mul_f32 v[234:235], v[112:113], s[98:99] op_sel:[0,1] op_sel_hi:[1,1]
	v_exp_f32_e32 v234, v234
	v_exp_f32_e32 v235, v235
	s_nop 0
	v_pk_add_f32 v[234:235], v[234:235], s[100:101] op_sel_hi:[1,0]
	v_rcp_f32_e32 v234, v234
	v_rcp_f32_e32 v235, v235
	s_nop 0
	v_pk_mul_f32 v[246:247], v[246:247], v[234:235]
	v_med3_f32 v7, v7, s40, v189
	s_nop 0
	v_mul_f32_e32 v9, v246, v108
	s_nop 0
	s_nop 0
	v_mul_f32_e32 v10, v247, v109
	v_pk_mul_f32 v[248:249], v[102:103], s[98:99] op_sel_hi:[1,0]
	v_pk_mul_f32 v[234:235], v[102:103], s[98:99] op_sel:[0,1] op_sel_hi:[1,1]
	v_exp_f32_e32 v234, v234
	v_exp_f32_e32 v235, v235
	s_nop 0
	v_pk_add_f32 v[234:235], v[234:235], s[100:101] op_sel_hi:[1,0]
	v_rcp_f32_e32 v234, v234
	v_rcp_f32_e32 v235, v235
	s_nop 0
	v_pk_mul_f32 v[248:249], v[248:249], v[234:235]
	s_nop 0
	s_nop 0
	v_mul_f32_e32 v11, v248, v98
	s_nop 0
	s_nop 0
	v_mul_f32_e32 v12, v249, v99
	v_pk_mul_f32 v[250:251], v[104:105], s[98:99] op_sel_hi:[1,0]
	v_pk_mul_f32 v[234:235], v[104:105], s[98:99] op_sel:[0,1] op_sel_hi:[1,1]
	v_exp_f32_e32 v234, v234
	v_exp_f32_e32 v235, v235
	s_nop 0
	v_pk_add_f32 v[234:235], v[234:235], s[100:101] op_sel_hi:[1,0]
	v_rcp_f32_e32 v234, v234
	v_rcp_f32_e32 v235, v235
	s_nop 0
	v_pk_mul_f32 v[250:251], v[250:251], v[234:235]
	s_nop 0
	s_nop 0
	v_mul_f32_e32 v13, v250, v100
	s_nop 0
	s_nop 0
	v_mov_b32_e32 v8, v163
	v_cvt_pk_fp8_f32 v8, v5, v7
	v_med3_f32 v5, v9, s40, v189
	v_med3_f32 v7, v10, s40, v189
	v_mov_b32_e32 v9, v163
	v_cvt_pk_fp8_f32 v8, v5, v7 op_sel:[0,0,1]
	v_med3_f32 v5, v11, s40, v189
	v_med3_f32 v7, v12, s40, v189
	v_cvt_pk_fp8_f32 v9, v5, v7
	v_mul_f32_e32 v14, v251, v101
	v_add_u32_e32 v6, 48, v4
	v_med3_f32 v5, v13, s40, v189
	v_med3_f32 v7, v14, s40, v189
	v_cvt_pk_fp8_f32 v9, v5, v7 op_sel:[0,0,1]
	v_ashrrev_i32_e32 v7, 31, v6
	v_lshlrev_b64 v[6:7], 7, v[6:7]
	v_lshl_add_u64 v[6:7], s[10:11], 0, v[6:7]
	v_lshl_add_u64 v[6:7], v[6:7], 0, v[2:3]
	v_pk_mul_f32 v[236:237], v[94:95], s[98:99] op_sel_hi:[1,0]
	v_pk_mul_f32 v[234:235], v[94:95], s[98:99] op_sel:[0,1] op_sel_hi:[1,1]
	v_exp_f32_e32 v234, v234
	v_exp_f32_e32 v235, v235
	s_nop 0
	v_pk_add_f32 v[234:235], v[234:235], s[100:101] op_sel_hi:[1,0]
	v_rcp_f32_e32 v234, v234
	v_rcp_f32_e32 v235, v235
	s_nop 0
	v_pk_mul_f32 v[236:237], v[236:237], v[234:235]
	global_store_dwordx2 v[6:7], v[8:9], off
	v_add_u32_e32 v6, 0x80, v4
	s_nop 0
	v_mul_f32_e32 v5, v236, v90
	v_med3_f32 v5, v5, s40, v189
	s_nop 0
	v_pk_mul_f32 v[238:239], v[96:97], s[98:99] op_sel_hi:[1,0]
	v_pk_mul_f32 v[234:235], v[96:97], s[98:99] op_sel:[0,1] op_sel_hi:[1,1]
	v_exp_f32_e32 v234, v234
	v_exp_f32_e32 v235, v235
	s_nop 0
	v_pk_add_f32 v[234:235], v[234:235], s[100:101] op_sel_hi:[1,0]
	v_rcp_f32_e32 v234, v234
	v_rcp_f32_e32 v235, v235
	s_nop 0
	v_pk_mul_f32 v[238:239], v[238:239], v[234:235]
	v_mul_f32_e32 v7, v237, v91
	v_med3_f32 v7, v7, s40, v189
	s_nop 0
	v_mul_f32_e32 v9, v238, v92
	s_nop 0
	s_nop 0
	v_mul_f32_e32 v10, v239, v93
	v_pk_mul_f32 v[240:241], v[86:87], s[98:99] op_sel_hi:[1,0]
	v_pk_mul_f32 v[234:235], v[86:87], s[98:99] op_sel:[0,1] op_sel_hi:[1,1]
	v_exp_f32_e32 v234, v234
	v_exp_f32_e32 v235, v235
	s_nop 0
	v_pk_add_f32 v[234:235], v[234:235], s[100:101] op_sel_hi:[1,0]
	v_rcp_f32_e32 v234, v234
	v_rcp_f32_e32 v235, v235
	s_nop 0
	v_pk_mul_f32 v[240:241], v[240:241], v[234:235]
	s_nop 0
	s_nop 0
	v_mul_f32_e32 v11, v240, v82
	s_nop 0
	s_nop 0
	v_mul_f32_e32 v12, v241, v83
	v_pk_mul_f32 v[242:243], v[88:89], s[98:99] op_sel_hi:[1,0]
	v_pk_mul_f32 v[234:235], v[88:89], s[98:99] op_sel:[0,1] op_sel_hi:[1,1]
	v_exp_f32_e32 v234, v234
	v_exp_f32_e32 v235, v235
	s_nop 0
	v_pk_add_f32 v[234:235], v[234:235], s[100:101] op_sel_hi:[1,0]
	v_rcp_f32_e32 v234, v234
	v_rcp_f32_e32 v235, v235
	s_nop 0
	v_pk_mul_f32 v[242:243], v[242:243], v[234:235]
	s_nop 0
	s_nop 0
	v_mul_f32_e32 v13, v242, v84
	s_nop 0
	s_nop 0
	v_mul_f32_e32 v14, v243, v85
	v_mov_b32_e32 v8, v163
	v_cvt_pk_fp8_f32 v8, v5, v7
	v_med3_f32 v5, v9, s40, v189
	v_med3_f32 v7, v10, s40, v189
	v_mov_b32_e32 v9, v163
	v_cvt_pk_fp8_f32 v8, v5, v7 op_sel:[0,0,1]
	v_med3_f32 v5, v11, s40, v189
	v_med3_f32 v7, v12, s40, v189
	v_cvt_pk_fp8_f32 v9, v5, v7
	v_med3_f32 v5, v13, s40, v189
	v_med3_f32 v7, v14, s40, v189
	v_cvt_pk_fp8_f32 v9, v5, v7 op_sel:[0,0,1]
	v_ashrrev_i32_e32 v7, 31, v6
	v_lshlrev_b64 v[6:7], 7, v[6:7]
	v_lshl_add_u64 v[6:7], s[10:11], 0, v[6:7]
	v_lshl_add_u64 v[6:7], v[6:7], 0, v[2:3]
	v_pk_mul_f32 v[244:245], v[78:79], s[98:99] op_sel_hi:[1,0]
	v_pk_mul_f32 v[234:235], v[78:79], s[98:99] op_sel:[0,1] op_sel_hi:[1,1]
	v_exp_f32_e32 v234, v234
	v_exp_f32_e32 v235, v235
	s_nop 0
	v_pk_add_f32 v[234:235], v[234:235], s[100:101] op_sel_hi:[1,0]
	v_rcp_f32_e32 v234, v234
	v_rcp_f32_e32 v235, v235
	s_nop 0
	v_pk_mul_f32 v[244:245], v[244:245], v[234:235]
	global_store_dwordx2 v[6:7], v[8:9], off
	s_nop 0
	s_nop 0
	v_mul_f32_e32 v5, v244, v74
	v_med3_f32 v5, v5, s40, v189
	s_nop 0
	v_mul_f32_e32 v7, v245, v75
	v_pk_mul_f32 v[246:247], v[80:81], s[98:99] op_sel_hi:[1,0]
	v_pk_mul_f32 v[234:235], v[80:81], s[98:99] op_sel:[0,1] op_sel_hi:[1,1]
	v_exp_f32_e32 v234, v234
	v_exp_f32_e32 v235, v235
	s_nop 0
	v_pk_add_f32 v[234:235], v[234:235], s[100:101] op_sel_hi:[1,0]
	v_rcp_f32_e32 v234, v234
	v_rcp_f32_e32 v235, v235
	s_nop 0
	v_pk_mul_f32 v[246:247], v[246:247], v[234:235]
	v_med3_f32 v7, v7, s40, v189
	s_nop 0
	v_mul_f32_e32 v9, v246, v76
	s_nop 0
	s_nop 0
	v_mul_f32_e32 v10, v247, v77
	v_pk_mul_f32 v[248:249], v[70:71], s[98:99] op_sel_hi:[1,0]
	v_pk_mul_f32 v[234:235], v[70:71], s[98:99] op_sel:[0,1] op_sel_hi:[1,1]
	v_exp_f32_e32 v234, v234
	v_exp_f32_e32 v235, v235
	s_nop 0
	v_pk_add_f32 v[234:235], v[234:235], s[100:101] op_sel_hi:[1,0]
	v_rcp_f32_e32 v234, v234
	v_rcp_f32_e32 v235, v235
	s_nop 0
	v_pk_mul_f32 v[248:249], v[248:249], v[234:235]
	s_nop 0
	s_nop 0
	v_mul_f32_e32 v11, v248, v66
	s_nop 0
	s_nop 0
	v_mul_f32_e32 v12, v249, v67
	v_pk_mul_f32 v[250:251], v[72:73], s[98:99] op_sel_hi:[1,0]
	v_pk_mul_f32 v[234:235], v[72:73], s[98:99] op_sel:[0,1] op_sel_hi:[1,1]
	v_exp_f32_e32 v234, v234
	v_exp_f32_e32 v235, v235
	s_nop 0
	v_pk_add_f32 v[234:235], v[234:235], s[100:101] op_sel_hi:[1,0]
	v_rcp_f32_e32 v234, v234
	v_rcp_f32_e32 v235, v235
	s_nop 0
	v_pk_mul_f32 v[250:251], v[250:251], v[234:235]
	s_nop 0
	s_nop 0
	v_mul_f32_e32 v13, v250, v68
	s_nop 0
	s_nop 0
	v_mov_b32_e32 v8, v163
	v_cvt_pk_fp8_f32 v8, v5, v7
	v_med3_f32 v5, v9, s40, v189
	v_med3_f32 v7, v10, s40, v189
	v_mov_b32_e32 v9, v163
	v_cvt_pk_fp8_f32 v8, v5, v7 op_sel:[0,0,1]
	v_med3_f32 v5, v11, s40, v189
	v_med3_f32 v7, v12, s40, v189
	v_cvt_pk_fp8_f32 v9, v5, v7
	v_mul_f32_e32 v14, v251, v69
	v_add_u32_e32 v6, 0x90, v4
	v_med3_f32 v5, v13, s40, v189
	v_med3_f32 v7, v14, s40, v189
	v_cvt_pk_fp8_f32 v9, v5, v7 op_sel:[0,0,1]
	v_ashrrev_i32_e32 v7, 31, v6
	v_lshlrev_b64 v[6:7], 7, v[6:7]
	v_lshl_add_u64 v[6:7], s[10:11], 0, v[6:7]
	v_lshl_add_u64 v[6:7], v[6:7], 0, v[2:3]
	v_pk_mul_f32 v[236:237], v[62:63], s[98:99] op_sel_hi:[1,0]
	v_pk_mul_f32 v[234:235], v[62:63], s[98:99] op_sel:[0,1] op_sel_hi:[1,1]
	v_exp_f32_e32 v234, v234
	v_exp_f32_e32 v235, v235
	s_nop 0
	v_pk_add_f32 v[234:235], v[234:235], s[100:101] op_sel_hi:[1,0]
	v_rcp_f32_e32 v234, v234
	v_rcp_f32_e32 v235, v235
	s_nop 0
	v_pk_mul_f32 v[236:237], v[236:237], v[234:235]
	global_store_dwordx2 v[6:7], v[8:9], off
	s_nop 0
	s_nop 0
	v_mul_f32_e32 v5, v236, v58
	v_med3_f32 v5, v5, s40, v189
	s_nop 0
	v_mul_f32_e32 v7, v237, v59
	v_pk_mul_f32 v[238:239], v[64:65], s[98:99] op_sel_hi:[1,0]
	v_pk_mul_f32 v[234:235], v[64:65], s[98:99] op_sel:[0,1] op_sel_hi:[1,1]
	v_exp_f32_e32 v234, v234
	v_exp_f32_e32 v235, v235
	s_nop 0
	v_pk_add_f32 v[234:235], v[234:235], s[100:101] op_sel_hi:[1,0]
	v_rcp_f32_e32 v234, v234
	v_rcp_f32_e32 v235, v235
	s_nop 0
	v_pk_mul_f32 v[238:239], v[238:239], v[234:235]
	v_med3_f32 v7, v7, s40, v189
	s_nop 0
	v_mul_f32_e32 v9, v238, v60
	s_nop 0
	s_nop 0
	v_mul_f32_e32 v10, v239, v61
	v_pk_mul_f32 v[240:241], v[54:55], s[98:99] op_sel_hi:[1,0]
	v_pk_mul_f32 v[234:235], v[54:55], s[98:99] op_sel:[0,1] op_sel_hi:[1,1]
	v_exp_f32_e32 v234, v234
	v_exp_f32_e32 v235, v235
	s_nop 0
	v_pk_add_f32 v[234:235], v[234:235], s[100:101] op_sel_hi:[1,0]
	v_rcp_f32_e32 v234, v234
	v_rcp_f32_e32 v235, v235
	s_nop 0
	v_pk_mul_f32 v[240:241], v[240:241], v[234:235]
	s_nop 0
	s_nop 0
	v_mul_f32_e32 v11, v240, v50
	s_nop 0
	s_nop 0
	v_mul_f32_e32 v12, v241, v51
	v_pk_mul_f32 v[242:243], v[56:57], s[98:99] op_sel_hi:[1,0]
	v_pk_mul_f32 v[234:235], v[56:57], s[98:99] op_sel:[0,1] op_sel_hi:[1,1]
	v_exp_f32_e32 v234, v234
	v_exp_f32_e32 v235, v235
	s_nop 0
	v_pk_add_f32 v[234:235], v[234:235], s[100:101] op_sel_hi:[1,0]
	v_rcp_f32_e32 v234, v234
	v_rcp_f32_e32 v235, v235
	s_nop 0
	v_pk_mul_f32 v[242:243], v[242:243], v[234:235]
	s_nop 0
	s_nop 0
	v_mul_f32_e32 v13, v242, v52
	s_nop 0
	s_nop 0
	v_mov_b32_e32 v8, v163
	v_cvt_pk_fp8_f32 v8, v5, v7
	v_med3_f32 v5, v9, s40, v189
	v_med3_f32 v7, v10, s40, v189
	v_mov_b32_e32 v9, v163
	v_cvt_pk_fp8_f32 v8, v5, v7 op_sel:[0,0,1]
	v_med3_f32 v5, v11, s40, v189
	v_med3_f32 v7, v12, s40, v189
	v_cvt_pk_fp8_f32 v9, v5, v7
	v_mul_f32_e32 v14, v243, v53
	v_add_u32_e32 v6, 0xa0, v4
	v_med3_f32 v5, v13, s40, v189
	v_med3_f32 v7, v14, s40, v189
	v_cvt_pk_fp8_f32 v9, v5, v7 op_sel:[0,0,1]
	v_ashrrev_i32_e32 v7, 31, v6
	v_lshlrev_b64 v[6:7], 7, v[6:7]
	v_lshl_add_u64 v[6:7], s[10:11], 0, v[6:7]
	v_lshl_add_u64 v[6:7], v[6:7], 0, v[2:3]
	v_pk_mul_f32 v[244:245], v[46:47], s[98:99] op_sel_hi:[1,0]
	v_pk_mul_f32 v[234:235], v[46:47], s[98:99] op_sel:[0,1] op_sel_hi:[1,1]
	v_exp_f32_e32 v234, v234
	v_exp_f32_e32 v235, v235
	s_nop 0
	v_pk_add_f32 v[234:235], v[234:235], s[100:101] op_sel_hi:[1,0]
	v_rcp_f32_e32 v234, v234
	v_rcp_f32_e32 v235, v235
	s_nop 0
	v_pk_mul_f32 v[244:245], v[244:245], v[234:235]
	global_store_dwordx2 v[6:7], v[8:9], off
	v_add_u32_e32 v4, 0xb0, v4
	s_nop 0
	v_mul_f32_e32 v5, v244, v42
	v_med3_f32 v5, v5, s40, v189
	s_nop 0
	v_pk_mul_f32 v[246:247], v[48:49], s[98:99] op_sel_hi:[1,0]
	v_pk_mul_f32 v[234:235], v[48:49], s[98:99] op_sel:[0,1] op_sel_hi:[1,1]
	v_exp_f32_e32 v234, v234
	v_exp_f32_e32 v235, v235
	s_nop 0
	v_pk_add_f32 v[234:235], v[234:235], s[100:101] op_sel_hi:[1,0]
	v_rcp_f32_e32 v234, v234
	v_rcp_f32_e32 v235, v235
	s_nop 0
	v_pk_mul_f32 v[246:247], v[246:247], v[234:235]
	v_mul_f32_e32 v6, v245, v43
	s_nop 0
	v_mul_f32_e32 v7, v246, v44
	s_nop 0
	v_pk_mul_f32 v[248:249], v[38:39], s[98:99] op_sel_hi:[1,0]
	v_pk_mul_f32 v[234:235], v[38:39], s[98:99] op_sel:[0,1] op_sel_hi:[1,1]
	v_exp_f32_e32 v234, v234
	v_exp_f32_e32 v235, v235
	s_nop 0
	v_pk_add_f32 v[234:235], v[234:235], s[100:101] op_sel_hi:[1,0]
	v_rcp_f32_e32 v234, v234
	v_rcp_f32_e32 v235, v235
	s_nop 0
	v_pk_mul_f32 v[248:249], v[248:249], v[234:235]
	v_mul_f32_e32 v8, v247, v45
	s_nop 0
	v_mul_f32_e32 v9, v248, v34
	s_nop 0
	v_pk_mul_f32 v[250:251], v[40:41], s[98:99] op_sel_hi:[1,0]
	v_pk_mul_f32 v[234:235], v[40:41], s[98:99] op_sel:[0,1] op_sel_hi:[1,1]
	v_exp_f32_e32 v234, v234
	v_exp_f32_e32 v235, v235
	s_nop 0
	v_pk_add_f32 v[234:235], v[234:235], s[100:101] op_sel_hi:[1,0]
	v_rcp_f32_e32 v234, v234
	v_rcp_f32_e32 v235, v235
	s_nop 0
	v_pk_mul_f32 v[250:251], v[250:251], v[234:235]
	v_mul_f32_e32 v10, v249, v35
	s_nop 0
	v_mul_f32_e32 v11, v250, v36
	s_nop 0
	v_med3_f32 v13, v6, s40, v189
	v_mov_b32_e32 v6, v163
	v_cvt_pk_fp8_f32 v6, v5, v13
	v_med3_f32 v5, v7, s40, v189
	v_med3_f32 v7, v8, s40, v189
	v_med3_f32 v8, v10, s40, v189
	v_cvt_pk_fp8_f32 v6, v5, v7 op_sel:[0,0,1]
	v_med3_f32 v5, v9, s40, v189
	v_mov_b32_e32 v7, v163
	v_cvt_pk_fp8_f32 v7, v5, v8
	v_mul_f32_e32 v12, v251, v37
	v_med3_f32 v5, v11, s40, v189
	v_med3_f32 v8, v12, s40, v189
	v_cvt_pk_fp8_f32 v7, v5, v8 op_sel:[0,0,1]
	v_ashrrev_i32_e32 v5, 31, v4
	v_lshlrev_b64 v[4:5], 7, v[4:5]
	v_lshl_add_u64 v[4:5], s[10:11], 0, v[4:5]
	v_lshl_add_u64 v[2:3], v[4:5], 0, v[2:3]
	global_store_dwordx2 v[2:3], v[6:7], off
	s_cbranch_vccz .LBB0_2738
	s_waitcnt vmcnt(0)
	s_cmpk_gt_u32 s42, 0xff
	s_cbranch_scc1 .LBB0_2684
	s_barrier
	s_branch .LBB0_2684
